# conv phase: non-temporal loads of its single-use input and rows visited in reverse order (most recently produced first)
# baseline (speedup 1.0000x reference)
; __device__ __forceinline__ int ltid(int wv) { unsigned z = 0u; asm volatile("" : "+v"(z)); return wv * 64 + (int)__builtin_amdgcn_mbcnt_hi(~0u, __builtin_amdgcn_mbcnt_lo(~0u, z)); }
; __device__ __forceinline__ int lgrid() { int g = gridDim.x; asm volatile("" : "+s"(g)); return g; }
; __device__ __forceinline__ int lbid() { int b = blockIdx.x; asm volatile("" : "+s"(b)); return b; }
; __device__ __forceinline__ void conv_pass(const bf16_t* __restrict__ U, const float* __restrict__ cw, const float* __restrict__ cb, bf16_t* __restrict__ GA, int tg, int wv) {
;     const int gt = lbid() * 512 + ltid(wv), NGT = lgrid() * 512;
;     constexpr int NCH = DFF / 8, RUN = 8; const int NITEM = (tg / RUN) * NCH;
;     for (int it = gt; it < NITEM; it += NGT) {
;         const int ch = it % NCH, run = it / NCH, c0 = ch * 8, t0 = run * RUN;
;         const u32x4 zero = {0u, 0u, 0u, 0u};
;         u32x4 ra[RUN + 2], rb[RUN + 2];
; #pragma unroll
;         for (int i = 0; i < RUN + 2; ++i) {
;             const int t = t0 - 1 + i;
;             const bool ok = !((i == 0 && (t0 & (SEQ - 1)) == 0) || (i == RUN + 1 && ((t0 + RUN) & (SEQ - 1)) == 0));
;             const bf16_t* p = U + (size_t)(ok ? t : t0) * DFF2 + c0;
;             const u32x4 a = *(const u32x4*)p, b = *(const u32x4*)(p + DFF);
;             ra[i] = ok ? a : zero; rb[i] = ok ? b : zero;
;         }
.LBB0_184:
	s_andn2_b64 vcc, exec, s[2:3]
	s_cbranch_vccnz .LBB0_269
	s_cmp_lt_i32 s63, 9
	s_mov_b64 s[2:3], -1
	s_cbranch_scc1 .LBB0_233
	s_cmp_gt_i32 s63, 9
	s_cbranch_scc0 .LBB0_191
	v_readlane_b32 s0, v255, 0
	v_mov_b32_e32 v0, v1
	s_lshl_b32 s0, s0, 9
	v_readlane_b32 s1, v255, 1
	v_readlane_b32 s2, v255, 16
	v_mbcnt_lo_u32_b32 v0, -1, v0
	s_add_i32 s0, s0, s1
	v_readlane_b32 s3, v255, 17
	v_mbcnt_hi_u32_b32 v0, -1, v0
	s_and_b64 s[2:3], s[2:3], exec
	s_mov_b32 s1, 0xb0000
	v_add_u32_e32 v0, s0, v0
	s_cselect_b32 s22, 0x160000, s1
	s_cselect_b32 s84, 12, 11
	s_lshl_b32 s84, 1, s84
	s_add_i32 s84, s84, -1
	s_mov_b32 s0, s33
	v_cmp_gt_i32_e32 vcc, s22, v0
	s_and_saveexec_b64 s[8:9], vcc
	s_cbranch_execz .LBB0_190
	v_readlane_b32 s2, v255, 12
	v_readlane_b32 s3, v255, 13
	s_load_dwordx4 s[64:67], s[2:3], 0x90
	s_add_u32 s12, s18, 0xa200000
	s_mul_i32 s1, s14, 0x10800
	s_addc_u32 s13, s19, 0
	s_mul_i32 s2, s14, 0x5800
	s_waitcnt lgkmcnt(0)
	s_add_u32 s64, s64, s1
	s_addc_u32 s65, s65, 0
	s_add_u32 s66, s66, s2
	s_addc_u32 s67, s67, 0
	s_add_u32 s68, s18, 0x20200000
	s_addc_u32 s69, s19, 0
	s_lshl_b32 s28, s0, 9
	s_add_u32 s70, s66, 0x2c00
	s_addc_u32 s71, s67, 0
	s_add_u32 s72, s64, 0x2c00
	s_addc_u32 s73, s65, 0
	s_add_u32 s74, s64, 0x5800
	s_addc_u32 s75, s65, 0
	s_add_u32 s76, s64, 0x8400
	s_addc_u32 s77, s65, 0
	s_add_u32 s78, s64, 0xb000
	s_addc_u32 s79, s65, 0
	s_add_u32 s80, s64, 0xdc00
	s_addc_u32 s81, s65, 0
	v_lshlrev_b32_e32 v154, 3, v0
	s_lshl_b32 s46, s0, 12
	s_mov_b64 s[82:83], 0
.LBB0_189:
	s_mov_b32 s0, 0x2e8ba2e9
	v_mul_hi_i32 v2, v0, s0
	v_lshrrev_b32_e32 v3, 31, v2
	v_ashrrev_i32_e32 v2, 6, v2
	v_add_u32_e32 v2, v2, v3
	v_mul_i32_i24_e32 v3, 0x160, v2
	v_lshlrev_b32_e32 v3, 3, v3
	v_sub_u32_e32 v10, v154, v3
	v_sub_u32_e32 v2, s84, v2
	v_lshlrev_b32_e32 v170, 3, v2
	v_and_b32_e32 v2, 0x3ff, v2
	v_ashrrev_i32_e32 v11, 31, v10
	v_lshlrev_b64 v[130:131], 1, v[10:11]
	v_cmp_ne_u32_e64 s[2:3], 0, v2
	v_add_u32_e32 v14, 8, v170
	v_lshl_add_u64 v[12:13], s[12:13], 0, v[130:131]
	v_subbrev_co_u32_e64 v2, s[4:5], 0, v170, s[2:3]
	v_and_b32_e32 v3, 0x1ff8, v14
	v_mad_i64_i32 v[6:7], s[0:1], v2, s95, v[12:13]
	v_cmp_eq_u32_e32 vcc, 0, v3
	global_load_dwordx4 v[2:5], v[6:7], off nt
	v_add_co_u32_e64 v6, s[4:5], s93, v6
	v_or_b32_e32 v169, 1, v170
	s_nop 0
	v_addc_co_u32_e64 v7, s[4:5], 0, v7, s[4:5]
	global_load_dwordx4 v[6:9], v[6:7], off offset:1536 nt
	v_or_b32_e32 v168, 2, v170
	v_or_b32_e32 v167, 3, v170
	v_or_b32_e32 v166, 4, v170
	v_or_b32_e32 v165, 5, v170
	v_or_b32_e32 v163, 6, v170
	v_or_b32_e32 v155, 7, v170
	v_lshl_add_u64 v[130:131], s[68:69], 0, v[130:131]
	v_add_u32_e32 v0, s28, v0
	v_add_u32_e32 v154, s46, v154
	s_waitcnt vmcnt(0)
	v_cndmask_b32_e64 v150, 0, v3, s[2:3]
	v_cndmask_b32_e64 v133, 0, v2, s[2:3]
	v_mad_i64_i32 v[2:3], s[0:1], v170, s95, v[12:13]
	v_cndmask_b32_e64 v152, 0, v5, s[2:3]
	v_cndmask_b32_e64 v138, 0, v4, s[2:3]
	global_load_dwordx4 v[118:121], v[2:3], off nt
	s_waitcnt vmcnt(1)
	v_cndmask_b32_e64 v171, 0, v9, s[2:3]
	v_cndmask_b32_e64 v153, 0, v8, s[2:3]
	v_cndmask_b32_e64 v139, 0, v7, s[2:3]
	v_cndmask_b32_e64 v140, 0, v6, s[2:3]
	v_add_co_u32_e64 v2, s[2:3], s93, v2
	v_lshlrev_b32_e32 v132, 16, v133
	s_nop 0
	v_addc_co_u32_e64 v3, s[2:3], 0, v3, s[2:3]
	global_load_dwordx4 v[114:117], v[2:3], off offset:1536 nt
	v_mad_i64_i32 v[2:3], s[0:1], v169, s95, v[12:13]
	global_load_dwordx4 v[126:129], v[2:3], off nt
	v_add_co_u32_e64 v2, s[2:3], s93, v2
	v_and_b32_e32 v133, 0xffff0000, v133
	s_nop 0
	v_addc_co_u32_e64 v3, s[2:3], 0, v3, s[2:3]
	global_load_dwordx4 v[122:125], v[2:3], off offset:1536 nt
	v_mad_i64_i32 v[2:3], s[0:1], v168, s95, v[12:13]
	global_load_dwordx4 v[110:113], v[2:3], off nt
	v_add_co_u32_e64 v2, s[2:3], s93, v2
	s_waitcnt vmcnt(4)
	v_lshlrev_b32_e32 v146, 16, v118
	v_addc_co_u32_e64 v3, s[2:3], 0, v3, s[2:3]
	global_load_dwordx4 v[106:109], v[2:3], off offset:1536 nt
	v_mad_i64_i32 v[2:3], s[0:1], v167, s95, v[12:13]
	global_load_dwordx4 v[102:105], v[2:3], off nt
	v_add_co_u32_e64 v2, s[2:3], s93, v2
	v_and_b32_e32 v147, 0xffff0000, v118
	s_nop 0
	v_addc_co_u32_e64 v3, s[2:3], 0, v3, s[2:3]
	global_load_dwordx4 v[98:101], v[2:3], off offset:1536 nt
	v_mad_i64_i32 v[2:3], s[0:1], v166, s95, v[12:13]
	global_load_dwordx4 v[94:97], v[2:3], off nt
	v_add_co_u32_e64 v2, s[2:3], s93, v2
	s_waitcnt vmcnt(7)
	v_and_b32_e32 v141, 0xffff0000, v114
	v_addc_co_u32_e64 v3, s[2:3], 0, v3, s[2:3]
	global_load_dwordx4 v[90:93], v[2:3], off offset:1536 nt
	v_mad_i64_i32 v[2:3], s[0:1], v165, s95, v[12:13]
	global_load_dwordx4 v[86:89], v[2:3], off nt
	v_add_co_u32_e64 v2, s[2:3], s93, v2
	v_and_b32_e32 v151, 0xffff0000, v120
	s_nop 0
	v_addc_co_u32_e64 v3, s[2:3], 0, v3, s[2:3]
	global_load_dwordx4 v[82:85], v[2:3], off offset:1536 nt
	v_mad_i64_i32 v[2:3], s[0:1], v163, s95, v[12:13]
	global_load_dwordx4 v[78:81], v[2:3], off nt
	v_add_co_u32_e64 v2, s[2:3], s93, v2
	s_nop 1
	v_addc_co_u32_e64 v3, s[2:3], 0, v3, s[2:3]
	global_load_dwordx4 v[74:77], v[2:3], off offset:1536 nt
	v_mad_i64_i32 v[2:3], s[0:1], v155, s95, v[12:13]
	global_load_dwordx4 v[70:73], v[2:3], off nt
	v_add_co_u32_e64 v2, s[2:3], s93, v2
	s_nop 1
	v_addc_co_u32_e64 v3, s[2:3], 0, v3, s[2:3]
	global_load_dwordx4 v[66:69], v[2:3], off offset:1536 nt
	v_cndmask_b32_e32 v2, v14, v170, vcc
	v_mad_i64_i32 v[6:7], s[0:1], v2, s95, v[12:13]
	global_load_dwordx4 v[2:5], v[6:7], off nt
	v_add_co_u32_e64 v6, s[2:3], s93, v6
	v_lshlrev_b64 v[14:15], 2, v[10:11]
	s_nop 0
	v_addc_co_u32_e64 v7, s[2:3], 0, v7, s[2:3]
	global_load_dwordx4 v[6:9], v[6:7], off offset:1536 nt
	v_lshl_add_u64 v[10:11], s[76:77], 0, v[14:15]
	v_lshl_add_u64 v[16:17], s[80:81], 0, v[14:15]
	v_lshl_add_u64 v[54:55], s[70:71], 0, v[14:15]
	s_waitcnt vmcnt(1)
; __device__ __forceinline__ float gelu_tanh(float x) { const float u = 0.7978845608028654f * (x + 0.044715f * x * x * x); return x * sigmoidf_(2.0f * u); }
; __device__ __forceinline__ float bfe(const u32x4& w, int e) { return (e & 1) ? __builtin_bit_cast(float, w[e >> 1] & 0xffff0000u) : __builtin_bit_cast(float, w[e >> 1] << 16); }
; __device__ __forceinline__ void conv_pass(const bf16_t* __restrict__ U, const float* __restrict__ cw, const float* __restrict__ cb, bf16_t* __restrict__ GA, int tg, int wv) {
;     ...
;         f32x4 wa[3][2], wb[3][2], ba[2], bb[2];
; #pragma unroll
;         for (int k = 0; k < 3; ++k) { wa[k][0] = *(const f32x4*)(cw + k * DFF2 + c0); wa[k][1] = *(const f32x4*)(cw + k * DFF2 + c0 + 4);
;                                       wb[k][0] = *(const f32x4*)(cw + k * DFF2 + DFF + c0); wb[k][1] = *(const f32x4*)(cw + k * DFF2 + DFF + c0 + 4); }
;         ba[0] = *(const f32x4*)(cb + c0); ba[1] = *(const f32x4*)(cb + c0 + 4); bb[0] = *(const f32x4*)(cb + DFF + c0); bb[1] = *(const f32x4*)(cb + DFF + c0 + 4);
; #pragma unroll
;         for (int i = 0; i < RUN; ++i) {
;             float o[8];
; #pragma unroll
;             for (int e = 0; e < 8; ++e) {
;                 const float ua = bfe(ra[i], e) * wa[0][e >> 2][e & 3] + bfe(ra[i + 1], e) * wa[1][e >> 2][e & 3] + bfe(ra[i + 2], e) * wa[2][e >> 2][e & 3] + ba[e >> 2][e & 3];
;                 const float ub = bfe(rb[i], e) * wb[0][e >> 2][e & 3] + bfe(rb[i + 1], e) * wb[1][e >> 2][e & 3] + bfe(rb[i + 2], e) * wb[2][e >> 2][e & 3] + bb[e >> 2][e & 3];
;                 o[e] = gelu_tanh(ua) * ub;
	v_cndmask_b32_e64 v161, v3, 0, vcc
	v_cndmask_b32_e64 v164, v2, 0, vcc
	v_lshl_add_u64 v[2:3], s[64:65], 0, v[14:15]
	v_cndmask_b32_e64 v157, v5, 0, vcc
	v_cndmask_b32_e64 v159, v4, 0, vcc
	global_load_dwordx4 v[18:21], v[2:3], off offset:16
	global_load_dwordx4 v[38:41], v[2:3], off
	s_waitcnt vmcnt(2)
	v_cndmask_b32_e64 v160, v7, 0, vcc
	v_cndmask_b32_e64 v162, v6, 0, vcc
	v_lshl_add_u64 v[6:7], s[72:73], 0, v[14:15]
	global_load_dwordx4 v[2:5], v[6:7], off offset:16
	global_load_dwordx4 v[34:37], v[6:7], off
	v_lshl_add_u64 v[6:7], s[74:75], 0, v[14:15]
	global_load_dwordx4 v[30:33], v[6:7], off offset:16
	global_load_dwordx4 v[50:53], v[6:7], off
	v_cndmask_b32_e64 v156, v9, 0, vcc
	v_cndmask_b32_e64 v158, v8, 0, vcc
	global_load_dwordx4 v[6:9], v[10:11], off offset:16
	global_load_dwordx4 v[42:45], v[10:11], off
	v_lshl_add_u64 v[10:11], s[78:79], 0, v[14:15]
	global_load_dwordx4 v[22:25], v[10:11], off offset:16
	global_load_dwordx4 v[58:61], v[10:11], off
	s_nop 0
	global_load_dwordx4 v[10:13], v[16:17], off offset:16
	global_load_dwordx4 v[46:49], v[16:17], off
	v_lshl_add_u64 v[16:17], s[66:67], 0, v[14:15]
	global_load_dwordx4 v[26:29], v[16:17], off offset:16
	global_load_dwordx4 v[62:65], v[16:17], off
	s_nop 0
	global_load_dwordx4 v[14:17], v[54:55], off offset:16
	s_nop 0
	global_load_dwordx4 v[54:57], v[54:55], off
	v_cmp_le_i32_e32 vcc, s22, v0
	s_or_b64 s[82:83], vcc, s[82:83]
	s_waitcnt vmcnt(10)
	v_pk_mul_f32 v[134:135], v[50:51], v[146:147]
	s_nop 0
	v_pk_fma_f32 v[132:133], v[38:39], v[132:133], v[134:135]
	v_lshlrev_b32_e32 v134, 16, v126
	v_and_b32_e32 v135, 0xffff0000, v126
	v_lshlrev_b32_e32 v126, 16, v139
	s_waitcnt vmcnt(6)
	v_pk_fma_f32 v[132:133], v[58:59], v[134:135], v[132:133]
	s_waitcnt vmcnt(2)
	v_pk_add_f32 v[136:137], v[132:133], v[62:63]
	s_nop 0
	v_mul_f32_e32 v118, 0x3d372713, v136
	v_lshlrev_b32_e32 v132, 16, v140
	v_and_b32_e32 v133, 0xffff0000, v140
	v_lshlrev_b32_e32 v140, 16, v114
	v_mul_f32_e32 v114, 0x3d372713, v137
	v_mul_f32_e32 v118, v136, v118
	v_mul_f32_e32 v114, v137, v114
	v_fma_f32 v118, v136, v118, v136
	v_fma_f32 v114, v137, v114, v137
	v_mul_f32_e32 v118, 0x3f4c422a, v118
	v_mul_f32_e32 v114, 0x3f4c422a, v114
	v_add_f32_e32 v118, v118, v118
	v_add_f32_e32 v114, v114, v114
	v_mul_f32_e32 v118, 0xbfb8aa3b, v118
	v_mul_f32_e32 v114, 0xbfb8aa3b, v114
	v_exp_f32_e32 v118, v118
	v_exp_f32_e32 v114, v114
	v_pk_mul_f32 v[144:145], v[42:43], v[140:141]
	v_add_f32_e32 v118, 1.0, v118
	v_add_f32_e32 v114, 1.0, v114
	v_rcp_f32_e32 v142, v118
	v_rcp_f32_e32 v143, v114
	v_pk_fma_f32 v[144:145], v[34:35], v[132:133], v[144:145]
	v_lshlrev_b32_e32 v132, 16, v122
	v_and_b32_e32 v133, 0xffff0000, v122
	v_pk_fma_f32 v[144:145], v[46:47], v[132:133], v[144:145]
	v_pk_mul_f32 v[136:137], v[136:137], v[142:143]
	s_waitcnt vmcnt(0)
	v_pk_add_f32 v[144:145], v[144:145], v[54:55]
	v_lshlrev_b32_e32 v142, 16, v115
	v_pk_mul_f32 v[148:149], v[144:145], v[136:137]
	v_lshlrev_b32_e32 v144, 16, v119
	v_and_b32_e32 v145, 0xffff0000, v119
	v_lshlrev_b32_e32 v136, 16, v150
	v_and_b32_e32 v137, 0xffff0000, v150
	v_pk_mul_f32 v[118:119], v[52:53], v[144:145]
	v_and_b32_e32 v143, 0xffff0000, v115
	v_pk_fma_f32 v[118:119], v[40:41], v[136:137], v[118:119]
	v_lshlrev_b32_e32 v136, 16, v127
	v_and_b32_e32 v137, 0xffff0000, v127
	v_pk_fma_f32 v[118:119], v[60:61], v[136:137], v[118:119]
	v_and_b32_e32 v127, 0xffff0000, v139
	v_pk_add_f32 v[118:119], v[118:119], v[64:65]
	v_lshlrev_b32_e32 v150, 16, v120
	v_mul_f32_e32 v114, 0x3d372713, v118
	v_mul_f32_e32 v114, v118, v114
	v_fma_f32 v114, v118, v114, v118
	v_mul_f32_e32 v114, 0x3f4c422a, v114
	v_add_f32_e32 v114, v114, v114
	v_mul_f32_e32 v114, 0xbfb8aa3b, v114
	v_exp_f32_e32 v114, v114
	v_and_b32_e32 v139, 0xffff0000, v128
	v_add_f32_e32 v114, 1.0, v114
	v_rcp_f32_e32 v122, v114
	v_pk_mul_f32 v[114:115], v[44:45], v[142:143]
	s_nop 0
	v_pk_fma_f32 v[126:127], v[36:37], v[126:127], v[114:115]
	v_lshlrev_b32_e32 v114, 16, v123
	v_and_b32_e32 v115, 0xffff0000, v123
	v_mul_f32_e32 v123, 0x3d372713, v119
	v_mul_f32_e32 v123, v119, v123
	v_fma_f32 v123, v119, v123, v119
	v_mul_f32_e32 v123, 0x3f4c422a, v123
	v_add_f32_e32 v123, v123, v123
	v_mul_f32_e32 v123, 0xbfb8aa3b, v123
	v_exp_f32_e32 v123, v123
	v_pk_fma_f32 v[126:127], v[48:49], v[114:115], v[126:127]
	v_add_f32_e32 v123, 1.0, v123
	v_rcp_f32_e32 v123, v123
	v_pk_add_f32 v[126:127], v[126:127], v[56:57]
	v_pk_mul_f32 v[118:119], v[118:119], v[122:123]
	s_nop 0
	v_pk_mul_f32 v[126:127], v[126:127], v[118:119]
	v_lshlrev_b32_e32 v118, 16, v138
	v_and_b32_e32 v119, 0xffff0000, v138
	v_pk_mul_f32 v[122:123], v[30:31], v[150:151]
	v_lshlrev_b32_e32 v138, 16, v128
	v_pk_fma_f32 v[118:119], v[18:19], v[118:119], v[122:123]
	v_lshlrev_b32_e32 v122, 16, v116
	v_pk_fma_f32 v[118:119], v[22:23], v[138:139], v[118:119]
	v_and_b32_e32 v123, 0xffff0000, v116
	v_pk_add_f32 v[172:173], v[118:119], v[26:27]
	v_and_b32_e32 v119, 0xffff0000, v153
	v_mul_f32_e32 v118, 0x3d372713, v172
	v_mul_f32_e32 v116, 0x3d372713, v173
	v_mul_f32_e32 v118, v172, v118
	v_mul_f32_e32 v116, v173, v116
	v_fma_f32 v118, v172, v118, v172
	v_fma_f32 v116, v173, v116, v173
	v_mul_f32_e32 v118, 0x3f4c422a, v118
	v_mul_f32_e32 v116, 0x3f4c422a, v116
	v_add_f32_e32 v118, v118, v118
	v_add_f32_e32 v116, v116, v116
	v_mul_f32_e32 v118, 0xbfb8aa3b, v118
	v_mul_f32_e32 v116, 0xbfb8aa3b, v116
	v_exp_f32_e32 v118, v118
	v_exp_f32_e32 v116, v116
	v_lshlrev_b32_e32 v128, 16, v129
	v_and_b32_e32 v129, 0xffff0000, v129
	v_add_f32_e32 v118, 1.0, v118
	v_add_f32_e32 v116, 1.0, v116
	v_rcp_f32_e32 v174, v118
	v_rcp_f32_e32 v175, v116
	v_lshlrev_b32_e32 v118, 16, v153
; __device__ __forceinline__ unsigned cvtpk(float lo, float hi) { f32x2 v = {lo, hi}; bf16x2_t b = __builtin_convertvector(v, bf16x2_t); return __builtin_bit_cast(unsigned, b); }
; __device__ __forceinline__ float gelu_tanh(float x) { const float u = 0.7978845608028654f * (x + 0.044715f * x * x * x); return x * sigmoidf_(2.0f * u); }
; __device__ __forceinline__ void st16_wt(void* p, u32x4 v) { asm volatile("global_store_dwordx4 %0, %1, off sc1\n\ts_nop 2" :: "v"(p), "v"(v) : "memory"); }
; __device__ __forceinline__ float bfe(const u32x4& w, int e) { return (e & 1) ? __builtin_bit_cast(float, w[e >> 1] & 0xffff0000u) : __builtin_bit_cast(float, w[e >> 1] << 16); }
; __device__ __forceinline__ void conv_pass(const bf16_t* __restrict__ U, const float* __restrict__ cw, const float* __restrict__ cb, bf16_t* __restrict__ GA, int tg, int wv) {
;     ...
;         for (int i = 0; i < RUN; ++i) {
;             float o[8];
; #pragma unroll
;             for (int e = 0; e < 8; ++e) {
;                 const float ua = bfe(ra[i], e) * wa[0][e >> 2][e & 3] + bfe(ra[i + 1], e) * wa[1][e >> 2][e & 3] + bfe(ra[i + 2], e) * wa[2][e >> 2][e & 3] + ba[e >> 2][e & 3];
;                 const float ub = bfe(rb[i], e) * wb[0][e >> 2][e & 3] + bfe(rb[i + 1], e) * wb[1][e >> 2][e & 3] + bfe(rb[i + 2], e) * wb[2][e >> 2][e & 3] + bb[e >> 2][e & 3];
;                 o[e] = gelu_tanh(ua) * ub;
;             }
;             u32x4 w; w.x = cvtpk(o[0], o[1]); w.y = cvtpk(o[2], o[3]); w.z = cvtpk(o[4], o[5]); w.w = cvtpk(o[6], o[7]);
;             st16_wt(GA + (size_t)(t0 + i) * DFF + c0, w);
	v_and_b32_e32 v153, 0xffff0000, v121
	v_pk_mul_f32 v[176:177], v[6:7], v[122:123]
	v_pk_mul_f32 v[172:173], v[172:173], v[174:175]
	v_lshlrev_b32_e32 v174, 16, v152
	v_and_b32_e32 v175, 0xffff0000, v152
	v_lshlrev_b32_e32 v152, 16, v121
	v_pk_mul_f32 v[120:121], v[32:33], v[152:153]
	v_pk_fma_f32 v[176:177], v[2:3], v[118:119], v[176:177]
	v_pk_fma_f32 v[120:121], v[20:21], v[174:175], v[120:121]
	v_lshlrev_b32_e32 v118, 16, v124
	v_pk_fma_f32 v[120:121], v[24:25], v[128:129], v[120:121]
	v_and_b32_e32 v119, 0xffff0000, v124
	v_pk_add_f32 v[174:175], v[120:121], v[28:29]
	v_pk_fma_f32 v[176:177], v[10:11], v[118:119], v[176:177]
	v_mul_f32_e32 v116, 0x3d372713, v174
	v_mul_f32_e32 v116, v174, v116
	v_fma_f32 v116, v174, v116, v174
	v_mul_f32_e32 v116, 0x3f4c422a, v116
	v_add_f32_e32 v116, v116, v116
	v_mul_f32_e32 v116, 0xbfb8aa3b, v116
	v_exp_f32_e32 v116, v116
	v_pk_add_f32 v[176:177], v[176:177], v[14:15]
	v_lshlrev_b32_e32 v120, 16, v117
	v_and_b32_e32 v121, 0xffff0000, v117
	v_add_f32_e32 v116, 1.0, v116
	v_pk_mul_f32 v[172:173], v[176:177], v[172:173]
	v_rcp_f32_e32 v124, v116
	v_lshlrev_b32_e32 v176, 16, v171
	v_and_b32_e32 v177, 0xffff0000, v171
	v_pk_mul_f32 v[116:117], v[8:9], v[120:121]
	s_nop 0
	v_pk_fma_f32 v[176:177], v[4:5], v[176:177], v[116:117]
	v_lshlrev_b32_e32 v116, 16, v125
	v_and_b32_e32 v117, 0xffff0000, v125
	v_mul_f32_e32 v125, 0x3d372713, v175
	v_mul_f32_e32 v125, v175, v125
	v_fma_f32 v125, v175, v125, v175
	v_mul_f32_e32 v125, 0x3f4c422a, v125
	v_add_f32_e32 v125, v125, v125
	v_mul_f32_e32 v125, 0xbfb8aa3b, v125
	v_exp_f32_e32 v125, v125
	v_pk_fma_f32 v[176:177], v[12:13], v[116:117], v[176:177]
	v_add_f32_e32 v125, 1.0, v125
	v_rcp_f32_e32 v125, v125
	v_pk_add_f32 v[176:177], v[176:177], v[16:17]
	v_pk_mul_f32 v[124:125], v[174:175], v[124:125]
	s_nop 0
	v_pk_mul_f32 v[174:175], v[176:177], v[124:125]
	v_cvt_pk_bf16_f32 v124, v148, v149
	v_cvt_pk_bf16_f32 v125, v126, v127
	v_cvt_pk_bf16_f32 v126, v172, v173
	v_cvt_pk_bf16_f32 v127, v174, v175
	v_mad_i64_i32 v[148:149], s[0:1], v170, s91, v[130:131]
	global_store_dwordx4 v[148:149], v[124:127], off sc1 nt
	s_nop 2
	v_pk_mul_f32 v[124:125], v[50:51], v[134:135]
	v_lshlrev_b32_e32 v148, 16, v110
	v_pk_fma_f32 v[124:125], v[38:39], v[146:147], v[124:125]
	v_and_b32_e32 v149, 0xffff0000, v110
	v_pk_fma_f32 v[124:125], v[58:59], v[148:149], v[124:125]
	v_pk_mul_f32 v[126:127], v[42:43], v[132:133]
	v_pk_add_f32 v[124:125], v[124:125], v[62:63]
	v_pk_fma_f32 v[140:141], v[34:35], v[140:141], v[126:127]
	v_mul_f32_e32 v110, 0x3d372713, v124
	v_lshlrev_b32_e32 v126, 16, v106
	v_and_b32_e32 v127, 0xffff0000, v106
	v_mul_f32_e32 v106, 0x3d372713, v125
	v_mul_f32_e32 v110, v124, v110
	v_mul_f32_e32 v106, v125, v106
	v_fma_f32 v110, v124, v110, v124
	v_fma_f32 v106, v125, v106, v125
	v_mul_f32_e32 v110, 0x3f4c422a, v110
	v_mul_f32_e32 v106, 0x3f4c422a, v106
	v_add_f32_e32 v110, v110, v110
	v_add_f32_e32 v106, v106, v106
	v_mul_f32_e32 v110, 0xbfb8aa3b, v110
	v_mul_f32_e32 v106, 0xbfb8aa3b, v106
	v_exp_f32_e32 v110, v110
	v_exp_f32_e32 v106, v106
	v_pk_fma_f32 v[140:141], v[46:47], v[126:127], v[140:141]
	v_add_f32_e32 v110, 1.0, v110
	v_add_f32_e32 v106, 1.0, v106
	v_rcp_f32_e32 v146, v110
	v_rcp_f32_e32 v147, v106
	v_pk_add_f32 v[140:141], v[140:141], v[54:55]
	v_pk_mul_f32 v[124:125], v[124:125], v[146:147]
	s_nop 0
	v_pk_mul_f32 v[146:147], v[140:141], v[124:125]
	v_pk_mul_f32 v[124:125], v[52:53], v[136:137]
	s_nop 0
	v_pk_fma_f32 v[124:125], v[40:41], v[144:145], v[124:125]
	v_lshlrev_b32_e32 v144, 16, v111
	v_and_b32_e32 v145, 0xffff0000, v111
	v_pk_fma_f32 v[110:111], v[60:61], v[144:145], v[124:125]
	v_pk_mul_f32 v[124:125], v[44:45], v[114:115]
	v_pk_add_f32 v[110:111], v[110:111], v[64:65]
	v_pk_fma_f32 v[140:141], v[36:37], v[142:143], v[124:125]
	v_mul_f32_e32 v106, 0x3d372713, v110
	v_lshlrev_b32_e32 v124, 16, v107
	v_and_b32_e32 v125, 0xffff0000, v107
	v_mul_f32_e32 v107, 0x3d372713, v111
	v_mul_f32_e32 v106, v110, v106
	v_mul_f32_e32 v107, v111, v107
	v_fma_f32 v106, v110, v106, v110
	v_fma_f32 v107, v111, v107, v111
	v_mul_f32_e32 v106, 0x3f4c422a, v106
	v_mul_f32_e32 v107, 0x3f4c422a, v107
	v_add_f32_e32 v106, v106, v106
	v_add_f32_e32 v107, v107, v107
	v_mul_f32_e32 v106, 0xbfb8aa3b, v106
	v_mul_f32_e32 v107, 0xbfb8aa3b, v107
	v_exp_f32_e32 v106, v106
	v_exp_f32_e32 v107, v107
	v_pk_fma_f32 v[140:141], v[48:49], v[124:125], v[140:141]
	v_lshlrev_b32_e32 v142, 16, v112
	v_add_f32_e32 v106, 1.0, v106
	v_add_f32_e32 v107, 1.0, v107
	v_rcp_f32_e32 v106, v106
	v_rcp_f32_e32 v107, v107
	v_pk_add_f32 v[140:141], v[140:141], v[56:57]
	v_and_b32_e32 v143, 0xffff0000, v112
	v_pk_mul_f32 v[106:107], v[110:111], v[106:107]
	s_nop 0
	v_pk_mul_f32 v[110:111], v[140:141], v[106:107]
	v_pk_mul_f32 v[106:107], v[30:31], v[138:139]
	s_nop 0
	v_pk_fma_f32 v[106:107], v[18:19], v[150:151], v[106:107]
	v_pk_mul_f32 v[150:151], v[6:7], v[118:119]
	v_pk_fma_f32 v[106:107], v[22:23], v[142:143], v[106:107]
	v_pk_fma_f32 v[150:151], v[2:3], v[122:123], v[150:151]
	v_pk_add_f32 v[106:107], v[106:107], v[26:27]
	v_lshlrev_b32_e32 v122, 16, v108
	v_mul_f32_e32 v112, 0x3d372713, v106
	v_and_b32_e32 v123, 0xffff0000, v108
	v_mul_f32_e32 v108, 0x3d372713, v107
	v_mul_f32_e32 v112, v106, v112
	v_mul_f32_e32 v108, v107, v108
	v_fma_f32 v112, v106, v112, v106
	v_fma_f32 v108, v107, v108, v107
	v_mul_f32_e32 v112, 0x3f4c422a, v112
	v_mul_f32_e32 v108, 0x3f4c422a, v108
	v_add_f32_e32 v112, v112, v112
	v_add_f32_e32 v108, v108, v108
	v_mul_f32_e32 v112, 0xbfb8aa3b, v112
	v_mul_f32_e32 v108, 0xbfb8aa3b, v108
	v_exp_f32_e32 v112, v112
	v_exp_f32_e32 v108, v108
; __device__ __forceinline__ unsigned cvtpk(float lo, float hi) { f32x2 v = {lo, hi}; bf16x2_t b = __builtin_convertvector(v, bf16x2_t); return __builtin_bit_cast(unsigned, b); }
; __device__ __forceinline__ float gelu_tanh(float x) { const float u = 0.7978845608028654f * (x + 0.044715f * x * x * x); return x * sigmoidf_(2.0f * u); }
; __device__ __forceinline__ void st16_wt(void* p, u32x4 v) { asm volatile("global_store_dwordx4 %0, %1, off sc1\n\ts_nop 2" :: "v"(p), "v"(v) : "memory"); }
; __device__ __forceinline__ float bfe(const u32x4& w, int e) { return (e & 1) ? __builtin_bit_cast(float, w[e >> 1] & 0xffff0000u) : __builtin_bit_cast(float, w[e >> 1] << 16); }
; __device__ __forceinline__ void conv_pass(const bf16_t* __restrict__ U, const float* __restrict__ cw, const float* __restrict__ cb, bf16_t* __restrict__ GA, int tg, int wv) {
;     ...
;         for (int i = 0; i < RUN; ++i) {
;             float o[8];
; #pragma unroll
;             for (int e = 0; e < 8; ++e) {
;                 const float ua = bfe(ra[i], e) * wa[0][e >> 2][e & 3] + bfe(ra[i + 1], e) * wa[1][e >> 2][e & 3] + bfe(ra[i + 2], e) * wa[2][e >> 2][e & 3] + ba[e >> 2][e & 3];
;                 const float ub = bfe(rb[i], e) * wb[0][e >> 2][e & 3] + bfe(rb[i + 1], e) * wb[1][e >> 2][e & 3] + bfe(rb[i + 2], e) * wb[2][e >> 2][e & 3] + bb[e >> 2][e & 3];
;                 o[e] = gelu_tanh(ua) * ub;
;             }
;             u32x4 w; w.x = cvtpk(o[0], o[1]); w.y = cvtpk(o[2], o[3]); w.z = cvtpk(o[4], o[5]); w.w = cvtpk(o[6], o[7]);
;             st16_wt(GA + (size_t)(t0 + i) * DFF + c0, w);
	v_pk_fma_f32 v[150:151], v[10:11], v[122:123], v[150:151]
	v_add_f32_e32 v112, 1.0, v112
	v_add_f32_e32 v108, 1.0, v108
	v_rcp_f32_e32 v140, v112
	v_rcp_f32_e32 v141, v108
	v_pk_add_f32 v[150:151], v[150:151], v[14:15]
	v_pk_mul_f32 v[106:107], v[106:107], v[140:141]
	s_nop 0
	v_pk_mul_f32 v[150:151], v[150:151], v[106:107]
	v_pk_mul_f32 v[106:107], v[32:33], v[128:129]
	v_lshlrev_b32_e32 v140, 16, v113
	v_pk_fma_f32 v[106:107], v[20:21], v[152:153], v[106:107]
	v_and_b32_e32 v141, 0xffff0000, v113
	v_pk_fma_f32 v[106:107], v[24:25], v[140:141], v[106:107]
	v_pk_mul_f32 v[112:113], v[8:9], v[116:117]
	v_pk_add_f32 v[106:107], v[106:107], v[28:29]
	v_pk_fma_f32 v[112:113], v[4:5], v[120:121], v[112:113]
	v_mul_f32_e32 v108, 0x3d372713, v106
	v_lshlrev_b32_e32 v120, 16, v109
	v_and_b32_e32 v121, 0xffff0000, v109
	v_mul_f32_e32 v109, 0x3d372713, v107
	v_mul_f32_e32 v108, v106, v108
	v_mul_f32_e32 v109, v107, v109
	v_fma_f32 v108, v106, v108, v106
	v_fma_f32 v109, v107, v109, v107
	v_mul_f32_e32 v108, 0x3f4c422a, v108
	v_mul_f32_e32 v109, 0x3f4c422a, v109
	v_add_f32_e32 v108, v108, v108
	v_add_f32_e32 v109, v109, v109
	v_mul_f32_e32 v108, 0xbfb8aa3b, v108
	v_mul_f32_e32 v109, 0xbfb8aa3b, v109
	v_exp_f32_e32 v108, v108
	v_exp_f32_e32 v109, v109
	v_pk_fma_f32 v[112:113], v[12:13], v[120:121], v[112:113]
	v_add_f32_e32 v108, 1.0, v108
	v_add_f32_e32 v109, 1.0, v109
	v_rcp_f32_e32 v108, v108
	v_rcp_f32_e32 v109, v109
	v_pk_add_f32 v[112:113], v[112:113], v[16:17]
	v_pk_mul_f32 v[106:107], v[106:107], v[108:109]
	s_nop 0
	v_pk_mul_f32 v[112:113], v[112:113], v[106:107]
	v_cvt_pk_bf16_f32 v106, v146, v147
	v_cvt_pk_bf16_f32 v107, v110, v111
	v_cvt_pk_bf16_f32 v108, v150, v151
	v_cvt_pk_bf16_f32 v109, v112, v113
	v_mad_i64_i32 v[110:111], s[0:1], v169, s91, v[130:131]
	global_store_dwordx4 v[110:111], v[106:109], off sc1 nt
	s_nop 2
	v_pk_mul_f32 v[106:107], v[50:51], v[148:149]
	v_lshlrev_b32_e32 v146, 16, v102
	v_pk_fma_f32 v[106:107], v[38:39], v[134:135], v[106:107]
	v_and_b32_e32 v147, 0xffff0000, v102
	v_pk_fma_f32 v[106:107], v[58:59], v[146:147], v[106:107]
	v_lshlrev_b32_e32 v112, 16, v98
	v_pk_add_f32 v[106:107], v[106:107], v[62:63]
	v_and_b32_e32 v113, 0xffff0000, v98
	v_mul_f32_e32 v102, 0x3d372713, v106
	v_mul_f32_e32 v98, 0x3d372713, v107
	v_mul_f32_e32 v102, v106, v102
	v_mul_f32_e32 v98, v107, v98
	v_fma_f32 v102, v106, v102, v106
	v_fma_f32 v98, v107, v98, v107
	v_mul_f32_e32 v102, 0x3f4c422a, v102
	v_mul_f32_e32 v98, 0x3f4c422a, v98
	v_add_f32_e32 v102, v102, v102
	v_add_f32_e32 v98, v98, v98
	v_mul_f32_e32 v102, 0xbfb8aa3b, v102
	v_mul_f32_e32 v98, 0xbfb8aa3b, v98
	v_exp_f32_e32 v102, v102
	v_exp_f32_e32 v98, v98
	v_lshlrev_b32_e32 v134, 16, v103
	v_and_b32_e32 v135, 0xffff0000, v103
	v_add_f32_e32 v102, 1.0, v102
	v_add_f32_e32 v98, 1.0, v98
	v_rcp_f32_e32 v108, v102
	v_rcp_f32_e32 v109, v98
	v_pk_mul_f32 v[110:111], v[42:43], v[126:127]
	v_pk_mul_f32 v[106:107], v[106:107], v[108:109]
	v_pk_mul_f32 v[108:109], v[52:53], v[144:145]
	v_pk_fma_f32 v[110:111], v[34:35], v[132:133], v[110:111]
	v_pk_fma_f32 v[108:109], v[40:41], v[136:137], v[108:109]
	v_pk_fma_f32 v[110:111], v[46:47], v[112:113], v[110:111]
	v_pk_fma_f32 v[102:103], v[60:61], v[134:135], v[108:109]
	v_pk_add_f32 v[110:111], v[110:111], v[54:55]
	v_pk_add_f32 v[102:103], v[102:103], v[64:65]
	v_pk_mul_f32 v[106:107], v[110:111], v[106:107]
	v_mul_f32_e32 v98, 0x3d372713, v102
	v_mul_f32_e32 v109, 0x3d372713, v103
	v_mul_f32_e32 v98, v102, v98
	v_mul_f32_e32 v109, v103, v109
	v_fma_f32 v98, v102, v98, v102
	v_fma_f32 v109, v103, v109, v103
	v_mul_f32_e32 v98, 0x3f4c422a, v98
	v_mul_f32_e32 v109, 0x3f4c422a, v109
	v_add_f32_e32 v98, v98, v98
	v_add_f32_e32 v109, v109, v109
	v_mul_f32_e32 v98, 0xbfb8aa3b, v98
	v_mul_f32_e32 v109, 0xbfb8aa3b, v109
	v_exp_f32_e32 v98, v98
	v_exp_f32_e32 v109, v109
	v_pk_mul_f32 v[110:111], v[44:45], v[124:125]
	v_lshlrev_b32_e32 v132, 16, v104
	v_add_f32_e32 v98, 1.0, v98
	v_add_f32_e32 v109, 1.0, v109
	v_rcp_f32_e32 v108, v98
	v_rcp_f32_e32 v109, v109
	v_pk_fma_f32 v[110:111], v[36:37], v[114:115], v[110:111]
	v_lshlrev_b32_e32 v98, 16, v99
	v_and_b32_e32 v99, 0xffff0000, v99
	v_pk_mul_f32 v[102:103], v[102:103], v[108:109]
	v_pk_mul_f32 v[108:109], v[30:31], v[142:143]
	v_pk_fma_f32 v[110:111], v[48:49], v[98:99], v[110:111]
	v_pk_fma_f32 v[108:109], v[18:19], v[138:139], v[108:109]
	v_and_b32_e32 v133, 0xffff0000, v104
	v_pk_add_f32 v[110:111], v[110:111], v[56:57]
	v_pk_fma_f32 v[108:109], v[22:23], v[132:133], v[108:109]
	v_pk_mul_f32 v[102:103], v[110:111], v[102:103]
	v_pk_add_f32 v[108:109], v[108:109], v[26:27]
	v_pk_mul_f32 v[110:111], v[6:7], v[122:123]
	v_mul_f32_e32 v104, 0x3d372713, v108
	v_pk_fma_f32 v[118:119], v[2:3], v[118:119], v[110:111]
	v_lshlrev_b32_e32 v110, 16, v100
	v_and_b32_e32 v111, 0xffff0000, v100
	v_mul_f32_e32 v100, 0x3d372713, v109
	v_mul_f32_e32 v104, v108, v104
	v_mul_f32_e32 v100, v109, v100
	v_fma_f32 v104, v108, v104, v108
	v_fma_f32 v100, v109, v100, v109
	v_mul_f32_e32 v104, 0x3f4c422a, v104
	v_mul_f32_e32 v100, 0x3f4c422a, v100
	v_add_f32_e32 v104, v104, v104
	v_add_f32_e32 v100, v100, v100
	v_mul_f32_e32 v104, 0xbfb8aa3b, v104
	v_mul_f32_e32 v100, 0xbfb8aa3b, v100
	v_exp_f32_e32 v104, v104
	v_exp_f32_e32 v100, v100
	v_pk_fma_f32 v[118:119], v[10:11], v[110:111], v[118:119]
	v_lshlrev_b32_e32 v136, 16, v94
	v_add_f32_e32 v104, 1.0, v104
	v_add_f32_e32 v100, 1.0, v100
	v_rcp_f32_e32 v114, v104
	v_rcp_f32_e32 v115, v100
	v_pk_add_f32 v[118:119], v[118:119], v[14:15]
	v_and_b32_e32 v137, 0xffff0000, v94
	v_pk_mul_f32 v[108:109], v[108:109], v[114:115]
	s_nop 0
	v_pk_mul_f32 v[114:115], v[118:119], v[108:109]
; __device__ __forceinline__ unsigned cvtpk(float lo, float hi) { f32x2 v = {lo, hi}; bf16x2_t b = __builtin_convertvector(v, bf16x2_t); return __builtin_bit_cast(unsigned, b); }
; __device__ __forceinline__ float gelu_tanh(float x) { const float u = 0.7978845608028654f * (x + 0.044715f * x * x * x); return x * sigmoidf_(2.0f * u); }
; __device__ __forceinline__ void st16_wt(void* p, u32x4 v) { asm volatile("global_store_dwordx4 %0, %1, off sc1\n\ts_nop 2" :: "v"(p), "v"(v) : "memory"); }
; __device__ __forceinline__ float bfe(const u32x4& w, int e) { return (e & 1) ? __builtin_bit_cast(float, w[e >> 1] & 0xffff0000u) : __builtin_bit_cast(float, w[e >> 1] << 16); }
; __device__ __forceinline__ void conv_pass(const bf16_t* __restrict__ U, const float* __restrict__ cw, const float* __restrict__ cb, bf16_t* __restrict__ GA, int tg, int wv) {
;     ...
;         for (int i = 0; i < RUN; ++i) {
;             float o[8];
; #pragma unroll
;             for (int e = 0; e < 8; ++e) {
;                 const float ua = bfe(ra[i], e) * wa[0][e >> 2][e & 3] + bfe(ra[i + 1], e) * wa[1][e >> 2][e & 3] + bfe(ra[i + 2], e) * wa[2][e >> 2][e & 3] + ba[e >> 2][e & 3];
;                 const float ub = bfe(rb[i], e) * wb[0][e >> 2][e & 3] + bfe(rb[i + 1], e) * wb[1][e >> 2][e & 3] + bfe(rb[i + 2], e) * wb[2][e >> 2][e & 3] + bb[e >> 2][e & 3];
;                 o[e] = gelu_tanh(ua) * ub;
;             }
;             u32x4 w; w.x = cvtpk(o[0], o[1]); w.y = cvtpk(o[2], o[3]); w.z = cvtpk(o[4], o[5]); w.w = cvtpk(o[6], o[7]);
;             st16_wt(GA + (size_t)(t0 + i) * DFF + c0, w);
	v_pk_mul_f32 v[108:109], v[32:33], v[140:141]
	v_lshlrev_b32_e32 v118, 16, v96
	v_pk_fma_f32 v[108:109], v[20:21], v[128:129], v[108:109]
	v_lshlrev_b32_e32 v128, 16, v105
	v_and_b32_e32 v129, 0xffff0000, v105
	v_pk_fma_f32 v[104:105], v[24:25], v[128:129], v[108:109]
	v_pk_mul_f32 v[108:109], v[8:9], v[120:121]
	v_pk_add_f32 v[104:105], v[104:105], v[28:29]
	v_pk_fma_f32 v[116:117], v[4:5], v[116:117], v[108:109]
	v_mul_f32_e32 v100, 0x3d372713, v104
	v_lshlrev_b32_e32 v108, 16, v101
	v_and_b32_e32 v109, 0xffff0000, v101
	v_mul_f32_e32 v101, 0x3d372713, v105
	v_mul_f32_e32 v100, v104, v100
	v_mul_f32_e32 v101, v105, v101
	v_fma_f32 v100, v104, v100, v104
	v_fma_f32 v101, v105, v101, v105
	v_mul_f32_e32 v100, 0x3f4c422a, v100
	v_mul_f32_e32 v101, 0x3f4c422a, v101
	v_add_f32_e32 v100, v100, v100
	v_add_f32_e32 v101, v101, v101
	v_mul_f32_e32 v100, 0xbfb8aa3b, v100
	v_mul_f32_e32 v101, 0xbfb8aa3b, v101
	v_exp_f32_e32 v100, v100
	v_exp_f32_e32 v101, v101
	v_pk_fma_f32 v[116:117], v[12:13], v[108:109], v[116:117]
	v_and_b32_e32 v119, 0xffff0000, v96
	v_add_f32_e32 v100, 1.0, v100
	v_add_f32_e32 v101, 1.0, v101
	v_rcp_f32_e32 v100, v100
	v_rcp_f32_e32 v101, v101
	v_pk_add_f32 v[116:117], v[116:117], v[16:17]
	v_pk_mul_f32 v[100:101], v[104:105], v[100:101]
	s_nop 0
	v_pk_mul_f32 v[104:105], v[116:117], v[100:101]
	v_cvt_pk_bf16_f32 v100, v106, v107
	v_cvt_pk_bf16_f32 v101, v102, v103
	v_cvt_pk_bf16_f32 v102, v114, v115
	v_cvt_pk_bf16_f32 v103, v104, v105
	v_mad_i64_i32 v[104:105], s[0:1], v168, s91, v[130:131]
	global_store_dwordx4 v[104:105], v[100:103], off sc1 nt
	s_nop 2
	v_pk_mul_f32 v[100:101], v[50:51], v[146:147]
	v_lshlrev_b32_e32 v106, 16, v90
	v_pk_fma_f32 v[100:101], v[38:39], v[148:149], v[100:101]
	v_and_b32_e32 v107, 0xffff0000, v90
	v_pk_fma_f32 v[100:101], v[58:59], v[136:137], v[100:101]
	v_pk_mul_f32 v[104:105], v[42:43], v[112:113]
	v_pk_add_f32 v[100:101], v[100:101], v[62:63]
	v_pk_fma_f32 v[104:105], v[34:35], v[126:127], v[104:105]
	v_mul_f32_e32 v94, 0x3d372713, v100
	v_mul_f32_e32 v90, 0x3d372713, v101
	v_mul_f32_e32 v94, v100, v94
	v_mul_f32_e32 v90, v101, v90
	v_fma_f32 v94, v100, v94, v100
	v_fma_f32 v90, v101, v90, v101
	v_mul_f32_e32 v94, 0x3f4c422a, v94
	v_mul_f32_e32 v90, 0x3f4c422a, v90
	v_add_f32_e32 v94, v94, v94
	v_add_f32_e32 v90, v90, v90
	v_mul_f32_e32 v94, 0xbfb8aa3b, v94
	v_mul_f32_e32 v90, 0xbfb8aa3b, v90
	v_exp_f32_e32 v94, v94
	v_exp_f32_e32 v90, v90
	v_lshlrev_b32_e32 v126, 16, v95
	v_and_b32_e32 v127, 0xffff0000, v95
	v_add_f32_e32 v94, 1.0, v94
	v_add_f32_e32 v90, 1.0, v90
	v_rcp_f32_e32 v102, v94
	v_rcp_f32_e32 v103, v90
	v_pk_fma_f32 v[104:105], v[46:47], v[106:107], v[104:105]
	v_pk_mul_f32 v[100:101], v[100:101], v[102:103]
	v_pk_mul_f32 v[102:103], v[52:53], v[134:135]
	v_pk_add_f32 v[104:105], v[104:105], v[54:55]
	v_pk_fma_f32 v[102:103], v[40:41], v[144:145], v[102:103]
	v_pk_mul_f32 v[100:101], v[104:105], v[100:101]
	v_pk_fma_f32 v[94:95], v[60:61], v[126:127], v[102:103]
	v_lshlrev_b32_e32 v104, 16, v91
	v_pk_add_f32 v[94:95], v[94:95], v[64:65]
	v_and_b32_e32 v105, 0xffff0000, v91
	v_mul_f32_e32 v90, 0x3d372713, v94
	v_mul_f32_e32 v91, 0x3d372713, v95
	v_mul_f32_e32 v90, v94, v90
	v_mul_f32_e32 v91, v95, v91
	v_fma_f32 v90, v94, v90, v94
	v_fma_f32 v91, v95, v91, v95
	v_mul_f32_e32 v90, 0x3f4c422a, v90
	v_mul_f32_e32 v91, 0x3f4c422a, v91
	v_add_f32_e32 v90, v90, v90
	v_add_f32_e32 v91, v91, v91
	v_mul_f32_e32 v90, 0xbfb8aa3b, v90
	v_mul_f32_e32 v91, 0xbfb8aa3b, v91
	v_exp_f32_e32 v90, v90
	v_exp_f32_e32 v91, v91
	v_pk_mul_f32 v[102:103], v[44:45], v[98:99]
	v_add_f32_e32 v90, 1.0, v90
	v_add_f32_e32 v91, 1.0, v91
	v_rcp_f32_e32 v90, v90
	v_rcp_f32_e32 v91, v91
	v_pk_fma_f32 v[102:103], v[36:37], v[124:125], v[102:103]
	v_pk_mul_f32 v[90:91], v[94:95], v[90:91]
	v_pk_fma_f32 v[102:103], v[48:49], v[104:105], v[102:103]
	s_nop 0
	v_pk_add_f32 v[102:103], v[102:103], v[56:57]
	s_nop 0
	v_pk_mul_f32 v[94:95], v[102:103], v[90:91]
	v_pk_mul_f32 v[90:91], v[30:31], v[132:133]
	s_nop 0
	v_pk_fma_f32 v[90:91], v[18:19], v[142:143], v[90:91]
	s_nop 0
	v_pk_fma_f32 v[90:91], v[22:23], v[118:119], v[90:91]
	s_nop 0
	v_pk_add_f32 v[102:103], v[90:91], v[26:27]
	s_nop 0
	v_mul_f32_e32 v90, 0x3d372713, v102
	v_mul_f32_e32 v90, v102, v90
	v_fma_f32 v90, v102, v90, v102
	v_mul_f32_e32 v90, 0x3f4c422a, v90
	v_add_f32_e32 v90, v90, v90
	v_mul_f32_e32 v90, 0xbfb8aa3b, v90
	v_exp_f32_e32 v90, v90
	s_nop 0
	v_add_f32_e32 v90, 1.0, v90
	v_rcp_f32_e32 v114, v90
	v_pk_mul_f32 v[90:91], v[6:7], v[110:111]
	s_nop 0
	v_pk_fma_f32 v[116:117], v[2:3], v[122:123], v[90:91]
	v_lshlrev_b32_e32 v90, 16, v92
	v_and_b32_e32 v91, 0xffff0000, v92
	v_mul_f32_e32 v92, 0x3d372713, v103
	v_mul_f32_e32 v92, v103, v92
	v_fma_f32 v92, v103, v92, v103
	v_mul_f32_e32 v92, 0x3f4c422a, v92
	v_add_f32_e32 v92, v92, v92
	v_mul_f32_e32 v92, 0xbfb8aa3b, v92
	v_exp_f32_e32 v92, v92
	v_pk_fma_f32 v[116:117], v[10:11], v[90:91], v[116:117]
	v_add_f32_e32 v92, 1.0, v92
	v_rcp_f32_e32 v115, v92
	v_pk_add_f32 v[116:117], v[116:117], v[14:15]
	v_pk_mul_f32 v[102:103], v[102:103], v[114:115]
	s_nop 0
	v_pk_mul_f32 v[114:115], v[116:117], v[102:103]
	v_pk_mul_f32 v[102:103], v[32:33], v[128:129]
	v_lshlrev_b32_e32 v116, 16, v97
	v_pk_fma_f32 v[102:103], v[20:21], v[140:141], v[102:103]
	v_and_b32_e32 v117, 0xffff0000, v97
	v_pk_fma_f32 v[96:97], v[24:25], v[116:117], v[102:103]
	v_pk_mul_f32 v[102:103], v[8:9], v[108:109]
	v_pk_add_f32 v[96:97], v[96:97], v[28:29]
	v_pk_fma_f32 v[120:121], v[4:5], v[120:121], v[102:103]
	v_mul_f32_e32 v92, 0x3d372713, v96
	v_lshlrev_b32_e32 v102, 16, v93
	v_and_b32_e32 v103, 0xffff0000, v93
; __device__ __forceinline__ unsigned cvtpk(float lo, float hi) { f32x2 v = {lo, hi}; bf16x2_t b = __builtin_convertvector(v, bf16x2_t); return __builtin_bit_cast(unsigned, b); }
; __device__ __forceinline__ float gelu_tanh(float x) { const float u = 0.7978845608028654f * (x + 0.044715f * x * x * x); return x * sigmoidf_(2.0f * u); }
; __device__ __forceinline__ void st16_wt(void* p, u32x4 v) { asm volatile("global_store_dwordx4 %0, %1, off sc1\n\ts_nop 2" :: "v"(p), "v"(v) : "memory"); }
; __device__ __forceinline__ float bfe(const u32x4& w, int e) { return (e & 1) ? __builtin_bit_cast(float, w[e >> 1] & 0xffff0000u) : __builtin_bit_cast(float, w[e >> 1] << 16); }
; __device__ __forceinline__ void conv_pass(const bf16_t* __restrict__ U, const float* __restrict__ cw, const float* __restrict__ cb, bf16_t* __restrict__ GA, int tg, int wv) {
;     ...
;         for (int i = 0; i < RUN; ++i) {
;             float o[8];
; #pragma unroll
;             for (int e = 0; e < 8; ++e) {
;                 const float ua = bfe(ra[i], e) * wa[0][e >> 2][e & 3] + bfe(ra[i + 1], e) * wa[1][e >> 2][e & 3] + bfe(ra[i + 2], e) * wa[2][e >> 2][e & 3] + ba[e >> 2][e & 3];
;                 const float ub = bfe(rb[i], e) * wb[0][e >> 2][e & 3] + bfe(rb[i + 1], e) * wb[1][e >> 2][e & 3] + bfe(rb[i + 2], e) * wb[2][e >> 2][e & 3] + bb[e >> 2][e & 3];
;                 o[e] = gelu_tanh(ua) * ub;
;             }
;             u32x4 w; w.x = cvtpk(o[0], o[1]); w.y = cvtpk(o[2], o[3]); w.z = cvtpk(o[4], o[5]); w.w = cvtpk(o[6], o[7]);
;             st16_wt(GA + (size_t)(t0 + i) * DFF + c0, w);
	v_mul_f32_e32 v93, 0x3d372713, v97
	v_mul_f32_e32 v92, v96, v92
	v_mul_f32_e32 v93, v97, v93
	v_fma_f32 v92, v96, v92, v96
	v_fma_f32 v93, v97, v93, v97
	v_mul_f32_e32 v92, 0x3f4c422a, v92
	v_mul_f32_e32 v93, 0x3f4c422a, v93
	v_add_f32_e32 v92, v92, v92
	v_add_f32_e32 v93, v93, v93
	v_mul_f32_e32 v92, 0xbfb8aa3b, v92
	v_mul_f32_e32 v93, 0xbfb8aa3b, v93
	v_exp_f32_e32 v92, v92
	v_exp_f32_e32 v93, v93
	v_pk_fma_f32 v[120:121], v[12:13], v[102:103], v[120:121]
	v_add_f32_e32 v92, 1.0, v92
	v_add_f32_e32 v93, 1.0, v93
	v_rcp_f32_e32 v92, v92
	v_rcp_f32_e32 v93, v93
	v_pk_add_f32 v[120:121], v[120:121], v[16:17]
	v_pk_mul_f32 v[92:93], v[96:97], v[92:93]
	s_nop 0
	v_pk_mul_f32 v[96:97], v[120:121], v[92:93]
	v_cvt_pk_bf16_f32 v92, v100, v101
	v_cvt_pk_bf16_f32 v93, v94, v95
	v_cvt_pk_bf16_f32 v94, v114, v115
	v_cvt_pk_bf16_f32 v95, v96, v97
	v_mad_i64_i32 v[96:97], s[0:1], v167, s91, v[130:131]
	global_store_dwordx4 v[96:97], v[92:95], off sc1 nt
	s_nop 2
	v_pk_mul_f32 v[92:93], v[50:51], v[136:137]
	v_lshlrev_b32_e32 v120, 16, v86
	v_pk_fma_f32 v[92:93], v[38:39], v[146:147], v[92:93]
	v_and_b32_e32 v121, 0xffff0000, v86
	v_pk_fma_f32 v[92:93], v[58:59], v[120:121], v[92:93]
	v_lshlrev_b32_e32 v100, 16, v82
	v_pk_add_f32 v[92:93], v[92:93], v[62:63]
	v_and_b32_e32 v101, 0xffff0000, v82
	v_mul_f32_e32 v86, 0x3d372713, v92
	v_mul_f32_e32 v82, 0x3d372713, v93
	v_mul_f32_e32 v86, v92, v86
	v_mul_f32_e32 v82, v93, v82
	v_fma_f32 v86, v92, v86, v92
	v_fma_f32 v82, v93, v82, v93
	v_mul_f32_e32 v86, 0x3f4c422a, v86
	v_mul_f32_e32 v82, 0x3f4c422a, v82
	v_add_f32_e32 v86, v86, v86
	v_add_f32_e32 v82, v82, v82
	v_mul_f32_e32 v86, 0xbfb8aa3b, v86
	v_mul_f32_e32 v82, 0xbfb8aa3b, v82
	v_exp_f32_e32 v86, v86
	v_exp_f32_e32 v82, v82
	v_lshlrev_b32_e32 v114, 16, v87
	v_and_b32_e32 v115, 0xffff0000, v87
	v_add_f32_e32 v86, 1.0, v86
	v_add_f32_e32 v82, 1.0, v82
	v_rcp_f32_e32 v94, v86
	v_rcp_f32_e32 v95, v82
	v_pk_mul_f32 v[96:97], v[42:43], v[106:107]
	v_pk_mul_f32 v[92:93], v[92:93], v[94:95]
	v_pk_mul_f32 v[94:95], v[52:53], v[126:127]
	v_pk_fma_f32 v[96:97], v[34:35], v[112:113], v[96:97]
	v_pk_fma_f32 v[94:95], v[40:41], v[134:135], v[94:95]
	v_pk_fma_f32 v[96:97], v[46:47], v[100:101], v[96:97]
	v_pk_fma_f32 v[86:87], v[60:61], v[114:115], v[94:95]
	v_pk_mul_f32 v[94:95], v[44:45], v[104:105]
	v_pk_add_f32 v[86:87], v[86:87], v[64:65]
	v_pk_fma_f32 v[94:95], v[36:37], v[98:99], v[94:95]
	v_mul_f32_e32 v82, 0x3d372713, v86
	v_lshlrev_b32_e32 v98, 16, v83
	v_and_b32_e32 v99, 0xffff0000, v83
	v_mul_f32_e32 v83, 0x3d372713, v87
	v_mul_f32_e32 v82, v86, v82
	v_mul_f32_e32 v83, v87, v83
	v_fma_f32 v82, v86, v82, v86
	v_fma_f32 v83, v87, v83, v87
	v_mul_f32_e32 v82, 0x3f4c422a, v82
	v_mul_f32_e32 v83, 0x3f4c422a, v83
	v_add_f32_e32 v82, v82, v82
	v_add_f32_e32 v83, v83, v83
	v_mul_f32_e32 v82, 0xbfb8aa3b, v82
	v_mul_f32_e32 v83, 0xbfb8aa3b, v83
	v_exp_f32_e32 v82, v82
	v_exp_f32_e32 v83, v83
	v_pk_fma_f32 v[94:95], v[48:49], v[98:99], v[94:95]
	v_lshlrev_b32_e32 v112, 16, v88
	v_add_f32_e32 v82, 1.0, v82
	v_add_f32_e32 v83, 1.0, v83
	v_rcp_f32_e32 v82, v82
	v_rcp_f32_e32 v83, v83
	v_pk_add_f32 v[94:95], v[94:95], v[56:57]
	v_and_b32_e32 v113, 0xffff0000, v88
	v_pk_add_f32 v[96:97], v[96:97], v[54:55]
	v_pk_mul_f32 v[82:83], v[86:87], v[82:83]
	v_pk_mul_f32 v[92:93], v[96:97], v[92:93]
	v_pk_mul_f32 v[86:87], v[94:95], v[82:83]
	v_pk_mul_f32 v[82:83], v[30:31], v[118:119]
	v_pk_mul_f32 v[96:97], v[6:7], v[90:91]
	v_pk_fma_f32 v[82:83], v[18:19], v[132:133], v[82:83]
	v_pk_fma_f32 v[110:111], v[2:3], v[110:111], v[96:97]
	v_pk_fma_f32 v[82:83], v[22:23], v[112:113], v[82:83]
	v_lshlrev_b32_e32 v96, 16, v84
	v_pk_add_f32 v[82:83], v[82:83], v[26:27]
	v_and_b32_e32 v97, 0xffff0000, v84
	v_mul_f32_e32 v88, 0x3d372713, v82
	v_mul_f32_e32 v84, 0x3d372713, v83
	v_mul_f32_e32 v88, v82, v88
	v_mul_f32_e32 v84, v83, v84
	v_fma_f32 v88, v82, v88, v82
	v_fma_f32 v84, v83, v84, v83
	v_mul_f32_e32 v88, 0x3f4c422a, v88
	v_mul_f32_e32 v84, 0x3f4c422a, v84
	v_add_f32_e32 v88, v88, v88
	v_add_f32_e32 v84, v84, v84
	v_mul_f32_e32 v88, 0xbfb8aa3b, v88
	v_mul_f32_e32 v84, 0xbfb8aa3b, v84
	v_exp_f32_e32 v88, v88
	v_exp_f32_e32 v84, v84
	v_pk_fma_f32 v[110:111], v[10:11], v[96:97], v[110:111]
	v_add_f32_e32 v88, 1.0, v88
	v_add_f32_e32 v84, 1.0, v84
	v_rcp_f32_e32 v94, v88
	v_rcp_f32_e32 v95, v84
	v_pk_add_f32 v[110:111], v[110:111], v[14:15]
	v_pk_mul_f32 v[82:83], v[82:83], v[94:95]
	s_nop 0
	v_pk_mul_f32 v[122:123], v[110:111], v[82:83]
	v_pk_mul_f32 v[82:83], v[32:33], v[116:117]
	v_lshlrev_b32_e32 v110, 16, v89
	v_pk_fma_f32 v[82:83], v[20:21], v[128:129], v[82:83]
	v_and_b32_e32 v111, 0xffff0000, v89
	v_pk_fma_f32 v[82:83], v[24:25], v[110:111], v[82:83]
	v_lshlrev_b32_e32 v94, 16, v85
	v_pk_add_f32 v[82:83], v[82:83], v[28:29]
	v_and_b32_e32 v95, 0xffff0000, v85
	v_mul_f32_e32 v84, 0x3d372713, v82
	v_mul_f32_e32 v85, 0x3d372713, v83
	v_mul_f32_e32 v84, v82, v84
	v_mul_f32_e32 v85, v83, v85
	v_fma_f32 v84, v82, v84, v82
	v_fma_f32 v85, v83, v85, v83
	v_mul_f32_e32 v84, 0x3f4c422a, v84
	v_mul_f32_e32 v85, 0x3f4c422a, v85
	v_add_f32_e32 v84, v84, v84
	v_add_f32_e32 v85, v85, v85
	v_mul_f32_e32 v84, 0xbfb8aa3b, v84
	v_mul_f32_e32 v85, 0xbfb8aa3b, v85
	v_exp_f32_e32 v84, v84
	v_exp_f32_e32 v85, v85
	v_pk_mul_f32 v[88:89], v[8:9], v[102:103]
	v_add_f32_e32 v84, 1.0, v84
	v_add_f32_e32 v85, 1.0, v85
	v_rcp_f32_e32 v84, v84
	v_rcp_f32_e32 v85, v85
	v_pk_fma_f32 v[88:89], v[4:5], v[108:109], v[88:89]
	v_pk_mul_f32 v[108:109], v[6:7], v[96:97]
	v_pk_fma_f32 v[88:89], v[12:13], v[94:95], v[88:89]
	v_pk_mul_f32 v[82:83], v[82:83], v[84:85]
	v_pk_add_f32 v[88:89], v[88:89], v[16:17]
; __device__ __forceinline__ unsigned cvtpk(float lo, float hi) { f32x2 v = {lo, hi}; bf16x2_t b = __builtin_convertvector(v, bf16x2_t); return __builtin_bit_cast(unsigned, b); }
; __device__ __forceinline__ float gelu_tanh(float x) { const float u = 0.7978845608028654f * (x + 0.044715f * x * x * x); return x * sigmoidf_(2.0f * u); }
; __device__ __forceinline__ void st16_wt(void* p, u32x4 v) { asm volatile("global_store_dwordx4 %0, %1, off sc1\n\ts_nop 2" :: "v"(p), "v"(v) : "memory"); }
; __device__ __forceinline__ float bfe(const u32x4& w, int e) { return (e & 1) ? __builtin_bit_cast(float, w[e >> 1] & 0xffff0000u) : __builtin_bit_cast(float, w[e >> 1] << 16); }
; __device__ __forceinline__ void conv_pass(const bf16_t* __restrict__ U, const float* __restrict__ cw, const float* __restrict__ cb, bf16_t* __restrict__ GA, int tg, int wv) {
;     ...
;         for (int i = 0; i < RUN; ++i) {
;             float o[8];
; #pragma unroll
;             for (int e = 0; e < 8; ++e) {
;                 const float ua = bfe(ra[i], e) * wa[0][e >> 2][e & 3] + bfe(ra[i + 1], e) * wa[1][e >> 2][e & 3] + bfe(ra[i + 2], e) * wa[2][e >> 2][e & 3] + ba[e >> 2][e & 3];
;                 const float ub = bfe(rb[i], e) * wb[0][e >> 2][e & 3] + bfe(rb[i + 1], e) * wb[1][e >> 2][e & 3] + bfe(rb[i + 2], e) * wb[2][e >> 2][e & 3] + bb[e >> 2][e & 3];
;                 o[e] = gelu_tanh(ua) * ub;
;             }
;             u32x4 w; w.x = cvtpk(o[0], o[1]); w.y = cvtpk(o[2], o[3]); w.z = cvtpk(o[4], o[5]); w.w = cvtpk(o[6], o[7]);
;             st16_wt(GA + (size_t)(t0 + i) * DFF + c0, w);
	v_cvt_pk_bf16_f32 v84, v122, v123
	v_pk_mul_f32 v[88:89], v[88:89], v[82:83]
	v_cvt_pk_bf16_f32 v82, v92, v93
	v_cvt_pk_bf16_f32 v83, v86, v87
	v_cvt_pk_bf16_f32 v85, v88, v89
	v_mad_i64_i32 v[86:87], s[0:1], v166, s91, v[130:131]
	global_store_dwordx4 v[86:87], v[82:85], off sc1 nt
	s_nop 2
	v_pk_mul_f32 v[82:83], v[50:51], v[120:121]
	v_lshlrev_b32_e32 v86, 16, v78
	v_pk_fma_f32 v[82:83], v[38:39], v[136:137], v[82:83]
	v_and_b32_e32 v87, 0xffff0000, v78
	v_pk_fma_f32 v[82:83], v[58:59], v[86:87], v[82:83]
	v_pk_fma_f32 v[108:109], v[2:3], v[90:91], v[108:109]
	v_pk_add_f32 v[84:85], v[82:83], v[62:63]
	v_pk_mul_f32 v[82:83], v[42:43], v[100:101]
	v_mul_f32_e32 v78, 0x3d372713, v84
	v_pk_fma_f32 v[92:93], v[34:35], v[106:107], v[82:83]
	v_lshlrev_b32_e32 v82, 16, v74
	v_and_b32_e32 v83, 0xffff0000, v74
	v_mul_f32_e32 v74, 0x3d372713, v85
	v_mul_f32_e32 v78, v84, v78
	v_mul_f32_e32 v74, v85, v74
	v_fma_f32 v78, v84, v78, v84
	v_fma_f32 v74, v85, v74, v85
	v_mul_f32_e32 v78, 0x3f4c422a, v78
	v_mul_f32_e32 v74, 0x3f4c422a, v74
	v_add_f32_e32 v78, v78, v78
	v_add_f32_e32 v74, v74, v74
	v_mul_f32_e32 v78, 0xbfb8aa3b, v78
	v_mul_f32_e32 v74, 0xbfb8aa3b, v74
	v_exp_f32_e32 v78, v78
	v_exp_f32_e32 v74, v74
	v_pk_fma_f32 v[92:93], v[46:47], v[82:83], v[92:93]
	v_lshlrev_b32_e32 v90, 16, v76
	v_add_f32_e32 v78, 1.0, v78
	v_add_f32_e32 v74, 1.0, v74
	v_rcp_f32_e32 v88, v78
	v_rcp_f32_e32 v89, v74
	v_pk_add_f32 v[92:93], v[92:93], v[54:55]
	v_and_b32_e32 v91, 0xffff0000, v76
	v_pk_fma_f32 v[108:109], v[10:11], v[90:91], v[108:109]
	v_pk_mul_f32 v[84:85], v[84:85], v[88:89]
	v_lshlrev_b32_e32 v88, 16, v79
	v_pk_mul_f32 v[106:107], v[92:93], v[84:85]
	v_pk_mul_f32 v[84:85], v[52:53], v[114:115]
	v_and_b32_e32 v89, 0xffff0000, v79
	v_pk_fma_f32 v[84:85], v[40:41], v[126:127], v[84:85]
	v_pk_add_f32 v[108:109], v[108:109], v[14:15]
	v_pk_fma_f32 v[78:79], v[60:61], v[88:89], v[84:85]
	v_pk_mul_f32 v[84:85], v[44:45], v[98:99]
	v_pk_add_f32 v[78:79], v[78:79], v[64:65]
	v_pk_fma_f32 v[92:93], v[36:37], v[104:105], v[84:85]
	v_mul_f32_e32 v74, 0x3d372713, v78
	v_lshlrev_b32_e32 v84, 16, v75
	v_and_b32_e32 v85, 0xffff0000, v75
	v_mul_f32_e32 v75, 0x3d372713, v79
	v_mul_f32_e32 v74, v78, v74
	v_mul_f32_e32 v75, v79, v75
	v_fma_f32 v74, v78, v74, v78
	v_fma_f32 v75, v79, v75, v79
	v_mul_f32_e32 v74, 0x3f4c422a, v74
	v_mul_f32_e32 v75, 0x3f4c422a, v75
	v_add_f32_e32 v74, v74, v74
	v_add_f32_e32 v75, v75, v75
	v_mul_f32_e32 v74, 0xbfb8aa3b, v74
	v_mul_f32_e32 v75, 0xbfb8aa3b, v75
	v_exp_f32_e32 v74, v74
	v_exp_f32_e32 v75, v75
	v_pk_fma_f32 v[92:93], v[48:49], v[84:85], v[92:93]
	v_add_f32_e32 v74, 1.0, v74
	v_add_f32_e32 v75, 1.0, v75
	v_rcp_f32_e32 v74, v74
	v_rcp_f32_e32 v75, v75
	v_pk_add_f32 v[92:93], v[92:93], v[56:57]
	v_pk_mul_f32 v[74:75], v[78:79], v[74:75]
	s_nop 0
	v_pk_mul_f32 v[104:105], v[92:93], v[74:75]
	v_pk_mul_f32 v[74:75], v[30:31], v[112:113]
	v_lshlrev_b32_e32 v92, 16, v80
	v_pk_fma_f32 v[74:75], v[18:19], v[118:119], v[74:75]
	v_and_b32_e32 v93, 0xffff0000, v80
	v_pk_fma_f32 v[74:75], v[22:23], v[92:93], v[74:75]
	s_nop 0
	v_pk_add_f32 v[74:75], v[74:75], v[26:27]
	s_nop 0
	v_mul_f32_e32 v78, 0x3d372713, v74
	v_mul_f32_e32 v76, 0x3d372713, v75
	v_mul_f32_e32 v78, v74, v78
	v_mul_f32_e32 v76, v75, v76
	v_fma_f32 v78, v74, v78, v74
	v_fma_f32 v76, v75, v76, v75
	v_mul_f32_e32 v78, 0x3f4c422a, v78
	v_mul_f32_e32 v76, 0x3f4c422a, v76
	v_add_f32_e32 v78, v78, v78
	v_add_f32_e32 v76, v76, v76
	v_mul_f32_e32 v78, 0xbfb8aa3b, v78
	v_mul_f32_e32 v76, 0xbfb8aa3b, v76
	v_exp_f32_e32 v78, v78
	v_exp_f32_e32 v76, v76
	v_add_f32_e32 v78, 1.0, v78
	v_add_f32_e32 v76, 1.0, v76
	v_rcp_f32_e32 v78, v78
	v_rcp_f32_e32 v79, v76
	s_nop 0
	v_pk_mul_f32 v[74:75], v[74:75], v[78:79]
	s_nop 0
	v_pk_mul_f32 v[108:109], v[108:109], v[74:75]
	v_pk_mul_f32 v[74:75], v[32:33], v[110:111]
	v_lshlrev_b32_e32 v78, 16, v81
	v_pk_fma_f32 v[74:75], v[20:21], v[116:117], v[74:75]
	v_and_b32_e32 v79, 0xffff0000, v81
	v_pk_fma_f32 v[74:75], v[24:25], v[78:79], v[74:75]
	s_nop 0
	v_pk_add_f32 v[80:81], v[74:75], v[28:29]
	s_nop 0
	v_mul_f32_e32 v74, 0x3d372713, v80
	v_mul_f32_e32 v74, v80, v74
	v_fma_f32 v74, v80, v74, v80
	v_mul_f32_e32 v74, 0x3f4c422a, v74
	v_add_f32_e32 v74, v74, v74
	v_mul_f32_e32 v74, 0xbfb8aa3b, v74
	v_exp_f32_e32 v74, v74
	s_nop 0
	v_add_f32_e32 v74, 1.0, v74
	v_rcp_f32_e32 v76, v74
	v_pk_mul_f32 v[74:75], v[8:9], v[94:95]
	s_nop 0
	v_pk_fma_f32 v[102:103], v[4:5], v[102:103], v[74:75]
	v_lshlrev_b32_e32 v74, 16, v77
	v_and_b32_e32 v75, 0xffff0000, v77
	v_mul_f32_e32 v77, 0x3d372713, v81
	v_mul_f32_e32 v77, v81, v77
	v_fma_f32 v77, v81, v77, v81
	v_mul_f32_e32 v77, 0x3f4c422a, v77
	v_add_f32_e32 v77, v77, v77
	v_mul_f32_e32 v77, 0xbfb8aa3b, v77
	v_exp_f32_e32 v77, v77
	v_pk_fma_f32 v[102:103], v[12:13], v[74:75], v[102:103]
	v_add_f32_e32 v77, 1.0, v77
	v_rcp_f32_e32 v77, v77
	v_pk_add_f32 v[102:103], v[102:103], v[16:17]
	v_pk_mul_f32 v[76:77], v[80:81], v[76:77]
	s_nop 0
	v_pk_mul_f32 v[76:77], v[102:103], v[76:77]
	v_cvt_pk_bf16_f32 v103, v104, v105
	v_cvt_pk_bf16_f32 v105, v76, v77
	v_mad_i64_i32 v[76:77], s[0:1], v165, s91, v[130:131]
	v_cvt_pk_bf16_f32 v102, v106, v107
	v_cvt_pk_bf16_f32 v104, v108, v109
	global_store_dwordx4 v[76:77], v[102:105], off sc1 nt
	s_nop 2
	v_pk_mul_f32 v[76:77], v[50:51], v[86:87]
	v_lshlrev_b32_e32 v80, 16, v70
	v_pk_fma_f32 v[76:77], v[38:39], v[120:121], v[76:77]
	v_and_b32_e32 v81, 0xffff0000, v70
	v_pk_fma_f32 v[76:77], v[58:59], v[80:81], v[76:77]
	v_pk_mul_f32 v[106:107], v[44:45], v[84:85]
	v_pk_add_f32 v[102:103], v[76:77], v[62:63]
	v_pk_mul_f32 v[76:77], v[42:43], v[82:83]
	v_mul_f32_e32 v70, 0x3d372713, v102
; __device__ __forceinline__ unsigned cvtpk(float lo, float hi) { f32x2 v = {lo, hi}; bf16x2_t b = __builtin_convertvector(v, bf16x2_t); return __builtin_bit_cast(unsigned, b); }
; __device__ __forceinline__ float gelu_tanh(float x) { const float u = 0.7978845608028654f * (x + 0.044715f * x * x * x); return x * sigmoidf_(2.0f * u); }
; __device__ __forceinline__ void st16_wt(void* p, u32x4 v) { asm volatile("global_store_dwordx4 %0, %1, off sc1\n\ts_nop 2" :: "v"(p), "v"(v) : "memory"); }
; __device__ __forceinline__ float bfe(const u32x4& w, int e) { return (e & 1) ? __builtin_bit_cast(float, w[e >> 1] & 0xffff0000u) : __builtin_bit_cast(float, w[e >> 1] << 16); }
; __device__ __forceinline__ void conv_pass(const bf16_t* __restrict__ U, const float* __restrict__ cw, const float* __restrict__ cb, bf16_t* __restrict__ GA, int tg, int wv) {
;     ...
;         for (int i = 0; i < RUN; ++i) {
;             float o[8];
; #pragma unroll
;             for (int e = 0; e < 8; ++e) {
;                 const float ua = bfe(ra[i], e) * wa[0][e >> 2][e & 3] + bfe(ra[i + 1], e) * wa[1][e >> 2][e & 3] + bfe(ra[i + 2], e) * wa[2][e >> 2][e & 3] + ba[e >> 2][e & 3];
;                 const float ub = bfe(rb[i], e) * wb[0][e >> 2][e & 3] + bfe(rb[i + 1], e) * wb[1][e >> 2][e & 3] + bfe(rb[i + 2], e) * wb[2][e >> 2][e & 3] + bb[e >> 2][e & 3];
;                 o[e] = gelu_tanh(ua) * ub;
;             }
;             u32x4 w; w.x = cvtpk(o[0], o[1]); w.y = cvtpk(o[2], o[3]); w.z = cvtpk(o[4], o[5]); w.w = cvtpk(o[6], o[7]);
;             st16_wt(GA + (size_t)(t0 + i) * DFF + c0, w);
	v_pk_fma_f32 v[100:101], v[34:35], v[100:101], v[76:77]
	v_lshlrev_b32_e32 v76, 16, v66
	v_and_b32_e32 v77, 0xffff0000, v66
	v_mul_f32_e32 v66, 0x3d372713, v103
	v_mul_f32_e32 v70, v102, v70
	v_mul_f32_e32 v66, v103, v66
	v_fma_f32 v70, v102, v70, v102
	v_fma_f32 v66, v103, v66, v103
	v_mul_f32_e32 v70, 0x3f4c422a, v70
	v_mul_f32_e32 v66, 0x3f4c422a, v66
	v_add_f32_e32 v70, v70, v70
	v_add_f32_e32 v66, v66, v66
	v_mul_f32_e32 v70, 0xbfb8aa3b, v70
	v_mul_f32_e32 v66, 0xbfb8aa3b, v66
	v_exp_f32_e32 v70, v70
	v_exp_f32_e32 v66, v66
	v_pk_fma_f32 v[100:101], v[46:47], v[76:77], v[100:101]
	v_pk_fma_f32 v[98:99], v[36:37], v[98:99], v[106:107]
	v_add_f32_e32 v70, 1.0, v70
	v_add_f32_e32 v66, 1.0, v66
	v_rcp_f32_e32 v104, v70
	v_rcp_f32_e32 v105, v66
	v_pk_add_f32 v[100:101], v[100:101], v[54:55]
	v_pk_mul_f32 v[108:109], v[6:7], v[90:91]
	v_pk_mul_f32 v[50:51], v[50:51], v[80:81]
	v_pk_mul_f32 v[102:103], v[102:103], v[104:105]
	v_pk_fma_f32 v[108:109], v[2:3], v[96:97], v[108:109]
	v_pk_mul_f32 v[102:103], v[100:101], v[102:103]
	v_pk_mul_f32 v[100:101], v[52:53], v[88:89]
	v_lshlrev_b32_e32 v96, 16, v68
	v_pk_fma_f32 v[104:105], v[40:41], v[114:115], v[100:101]
	v_lshlrev_b32_e32 v100, 16, v71
	v_and_b32_e32 v101, 0xffff0000, v71
	v_pk_fma_f32 v[70:71], v[60:61], v[100:101], v[104:105]
	v_and_b32_e32 v97, 0xffff0000, v68
	v_pk_add_f32 v[70:71], v[70:71], v[64:65]
	v_pk_fma_f32 v[38:39], v[38:39], v[86:87], v[50:51]
	v_mul_f32_e32 v66, 0x3d372713, v70
	v_mul_f32_e32 v105, 0x3d372713, v71
	v_mul_f32_e32 v66, v70, v66
	v_mul_f32_e32 v105, v71, v105
	v_fma_f32 v66, v70, v66, v70
	v_fma_f32 v105, v71, v105, v71
	v_mul_f32_e32 v66, 0x3f4c422a, v66
	v_mul_f32_e32 v105, 0x3f4c422a, v105
	v_add_f32_e32 v66, v66, v66
	v_add_f32_e32 v105, v105, v105
	v_mul_f32_e32 v66, 0xbfb8aa3b, v66
	v_mul_f32_e32 v105, 0xbfb8aa3b, v105
	v_exp_f32_e32 v66, v66
	v_exp_f32_e32 v105, v105
	v_lshlrev_b32_e32 v50, 16, v164
	v_and_b32_e32 v51, 0xffff0000, v164
	v_add_f32_e32 v66, 1.0, v66
	v_add_f32_e32 v105, 1.0, v105
	v_rcp_f32_e32 v104, v66
	v_rcp_f32_e32 v105, v105
	v_lshlrev_b32_e32 v66, 16, v67
	v_and_b32_e32 v67, 0xffff0000, v67
	v_pk_fma_f32 v[98:99], v[48:49], v[66:67], v[98:99]
	v_pk_mul_f32 v[70:71], v[70:71], v[104:105]
	v_pk_add_f32 v[98:99], v[98:99], v[56:57]
	v_pk_fma_f32 v[38:39], v[58:59], v[50:51], v[38:39]
	v_pk_mul_f32 v[104:105], v[98:99], v[70:71]
	v_pk_mul_f32 v[70:71], v[30:31], v[92:93]
	v_lshlrev_b32_e32 v98, 16, v72
	v_pk_fma_f32 v[70:71], v[18:19], v[112:113], v[70:71]
	v_and_b32_e32 v99, 0xffff0000, v72
	v_pk_fma_f32 v[70:71], v[22:23], v[98:99], v[70:71]
	v_pk_mul_f32 v[30:31], v[30:31], v[98:99]
	v_pk_add_f32 v[70:71], v[70:71], v[26:27]
	v_pk_fma_f32 v[18:19], v[18:19], v[92:93], v[30:31]
	v_mul_f32_e32 v72, 0x3d372713, v70
	v_mul_f32_e32 v68, 0x3d372713, v71
	v_mul_f32_e32 v72, v70, v72
	v_mul_f32_e32 v68, v71, v68
	v_fma_f32 v72, v70, v72, v70
	v_fma_f32 v68, v71, v68, v71
	v_mul_f32_e32 v72, 0x3f4c422a, v72
	v_mul_f32_e32 v68, 0x3f4c422a, v68
	v_add_f32_e32 v72, v72, v72
	v_add_f32_e32 v68, v68, v68
	v_mul_f32_e32 v72, 0xbfb8aa3b, v72
	v_mul_f32_e32 v68, 0xbfb8aa3b, v68
	v_exp_f32_e32 v72, v72
	v_exp_f32_e32 v68, v68
	v_lshlrev_b32_e32 v30, 16, v159
	v_and_b32_e32 v31, 0xffff0000, v159
	v_add_f32_e32 v72, 1.0, v72
	v_add_f32_e32 v68, 1.0, v68
	v_rcp_f32_e32 v106, v72
	v_rcp_f32_e32 v107, v68
	v_pk_mul_f32 v[42:43], v[42:43], v[76:77]
	v_pk_fma_f32 v[18:19], v[22:23], v[30:31], v[18:19]
	v_pk_mul_f32 v[6:7], v[6:7], v[96:97]
	v_pk_add_f32 v[38:39], v[38:39], v[62:63]
	v_pk_fma_f32 v[34:35], v[34:35], v[82:83], v[42:43]
	v_lshlrev_b32_e32 v42, 16, v162
	v_and_b32_e32 v43, 0xffff0000, v162
	v_pk_add_f32 v[18:19], v[18:19], v[26:27]
	v_pk_fma_f32 v[2:3], v[2:3], v[90:91], v[6:7]
	v_lshlrev_b32_e32 v6, 16, v158
	v_and_b32_e32 v7, 0xffff0000, v158
	v_pk_fma_f32 v[108:109], v[10:11], v[96:97], v[108:109]
	v_mul_f32_e32 v50, 0x3d372713, v38
	v_pk_fma_f32 v[34:35], v[46:47], v[42:43], v[34:35]
	v_mul_f32_e32 v42, 0x3d372713, v39
	v_mul_f32_e32 v22, 0x3d372713, v18
	v_pk_fma_f32 v[2:3], v[10:11], v[6:7], v[2:3]
	v_mul_f32_e32 v6, 0x3d372713, v19
	v_pk_add_f32 v[108:109], v[108:109], v[14:15]
	v_pk_mul_f32 v[70:71], v[70:71], v[106:107]
	v_mul_f32_e32 v50, v38, v50
	v_mul_f32_e32 v42, v39, v42
	v_mul_f32_e32 v22, v18, v22
	v_mul_f32_e32 v6, v19, v6
	v_pk_mul_f32 v[106:107], v[108:109], v[70:71]
	v_pk_mul_f32 v[70:71], v[32:33], v[78:79]
	v_fma_f32 v50, v38, v50, v38
	v_fma_f32 v42, v39, v42, v39
	v_fma_f32 v22, v18, v22, v18
	v_fma_f32 v6, v19, v6, v19
	v_pk_fma_f32 v[108:109], v[20:21], v[110:111], v[70:71]
	v_lshlrev_b32_e32 v70, 16, v73
	v_and_b32_e32 v71, 0xffff0000, v73
	v_mul_f32_e32 v50, 0x3f4c422a, v50
; __device__ __forceinline__ unsigned cvtpk(float lo, float hi) { f32x2 v = {lo, hi}; bf16x2_t b = __builtin_convertvector(v, bf16x2_t); return __builtin_bit_cast(unsigned, b); }
; __device__ __forceinline__ float gelu_tanh(float x) { const float u = 0.7978845608028654f * (x + 0.044715f * x * x * x); return x * sigmoidf_(2.0f * u); }
; __device__ __forceinline__ void st16_wt(void* p, u32x4 v) { asm volatile("global_store_dwordx4 %0, %1, off sc1\n\ts_nop 2" :: "v"(p), "v"(v) : "memory"); }
; __device__ __forceinline__ float bfe(const u32x4& w, int e) { return (e & 1) ? __builtin_bit_cast(float, w[e >> 1] & 0xffff0000u) : __builtin_bit_cast(float, w[e >> 1] << 16); }
; __device__ __forceinline__ void conv_pass(const bf16_t* __restrict__ U, const float* __restrict__ cw, const float* __restrict__ cb, bf16_t* __restrict__ GA, int tg, int wv) {
;     ...
;         for (int i = 0; i < RUN; ++i) {
;             float o[8];
; #pragma unroll
;             for (int e = 0; e < 8; ++e) {
;                 const float ua = bfe(ra[i], e) * wa[0][e >> 2][e & 3] + bfe(ra[i + 1], e) * wa[1][e >> 2][e & 3] + bfe(ra[i + 2], e) * wa[2][e >> 2][e & 3] + ba[e >> 2][e & 3];
;                 const float ub = bfe(rb[i], e) * wb[0][e >> 2][e & 3] + bfe(rb[i + 1], e) * wb[1][e >> 2][e & 3] + bfe(rb[i + 2], e) * wb[2][e >> 2][e & 3] + bb[e >> 2][e & 3];
;                 o[e] = gelu_tanh(ua) * ub;
;             }
;             u32x4 w; w.x = cvtpk(o[0], o[1]); w.y = cvtpk(o[2], o[3]); w.z = cvtpk(o[4], o[5]); w.w = cvtpk(o[6], o[7]);
;             st16_wt(GA + (size_t)(t0 + i) * DFF + c0, w);
;         }
;     }
	v_mul_f32_e32 v42, 0x3f4c422a, v42
	v_mul_f32_e32 v22, 0x3f4c422a, v22
	v_mul_f32_e32 v6, 0x3f4c422a, v6
	v_pk_fma_f32 v[72:73], v[24:25], v[70:71], v[108:109]
	v_add_f32_e32 v50, v50, v50
	v_add_f32_e32 v42, v42, v42
	v_add_f32_e32 v22, v22, v22
	v_add_f32_e32 v6, v6, v6
	v_pk_add_f32 v[72:73], v[72:73], v[28:29]
	v_mul_f32_e32 v50, 0xbfb8aa3b, v50
	v_mul_f32_e32 v42, 0xbfb8aa3b, v42
	v_mul_f32_e32 v22, 0xbfb8aa3b, v22
	v_mul_f32_e32 v6, 0xbfb8aa3b, v6
	v_mul_f32_e32 v68, 0x3d372713, v72
	v_exp_f32_e32 v50, v50
	v_exp_f32_e32 v42, v42
	v_exp_f32_e32 v22, v22
	v_exp_f32_e32 v6, v6
	v_mul_f32_e32 v68, v72, v68
	v_fma_f32 v68, v72, v68, v72
	v_mul_f32_e32 v68, 0x3f4c422a, v68
	v_add_f32_e32 v68, v68, v68
	v_add_f32_e32 v50, 1.0, v50
	v_add_f32_e32 v42, 1.0, v42
	v_add_f32_e32 v22, 1.0, v22
	v_add_f32_e32 v6, 1.0, v6
	v_mul_f32_e32 v68, 0xbfb8aa3b, v68
	v_rcp_f32_e32 v50, v50
	v_rcp_f32_e32 v51, v42
	v_rcp_f32_e32 v22, v22
	v_rcp_f32_e32 v23, v6
	v_exp_f32_e32 v68, v68
	v_pk_add_f32 v[34:35], v[34:35], v[54:55]
	v_pk_mul_f32 v[38:39], v[38:39], v[50:51]
	v_pk_add_f32 v[2:3], v[2:3], v[14:15]
	v_pk_mul_f32 v[6:7], v[18:19], v[22:23]
	v_add_f32_e32 v68, 1.0, v68
	v_pk_mul_f32 v[34:35], v[34:35], v[38:39]
	v_pk_mul_f32 v[38:39], v[52:53], v[100:101]
	v_pk_mul_f32 v[2:3], v[2:3], v[6:7]
	v_pk_mul_f32 v[6:7], v[32:33], v[70:71]
	v_rcp_f32_e32 v108, v68
	v_lshlrev_b32_e32 v68, 16, v69
	v_and_b32_e32 v69, 0xffff0000, v69
	v_pk_fma_f32 v[38:39], v[40:41], v[88:89], v[38:39]
	v_lshlrev_b32_e32 v40, 16, v161
	v_and_b32_e32 v41, 0xffff0000, v161
	v_pk_fma_f32 v[6:7], v[20:21], v[78:79], v[6:7]
	v_lshlrev_b32_e32 v10, 16, v157
	v_and_b32_e32 v11, 0xffff0000, v157
	v_pk_mul_f32 v[110:111], v[8:9], v[74:75]
	v_pk_fma_f32 v[38:39], v[60:61], v[40:41], v[38:39]
	v_pk_fma_f32 v[6:7], v[24:25], v[10:11], v[6:7]
	v_pk_mul_f32 v[8:9], v[8:9], v[68:69]
	v_pk_fma_f32 v[94:95], v[4:5], v[94:95], v[110:111]
	v_mul_f32_e32 v109, 0x3d372713, v73
	v_pk_add_f32 v[38:39], v[38:39], v[64:65]
	v_pk_add_f32 v[6:7], v[6:7], v[28:29]
	v_pk_fma_f32 v[4:5], v[4:5], v[74:75], v[8:9]
	v_lshlrev_b32_e32 v8, 16, v156
	v_and_b32_e32 v9, 0xffff0000, v156
	v_mul_f32_e32 v109, v73, v109
	v_mul_f32_e32 v40, 0x3d372713, v38
	v_mul_f32_e32 v41, 0x3d372713, v39
	v_mul_f32_e32 v10, 0x3d372713, v6
	v_pk_fma_f32 v[4:5], v[12:13], v[8:9], v[4:5]
	v_mul_f32_e32 v8, 0x3d372713, v7
	v_fma_f32 v109, v73, v109, v73
	v_mul_f32_e32 v40, v38, v40
	v_mul_f32_e32 v41, v39, v41
	v_mul_f32_e32 v10, v6, v10
	v_mul_f32_e32 v8, v7, v8
	v_mul_f32_e32 v109, 0x3f4c422a, v109
	v_fma_f32 v40, v38, v40, v38
	v_fma_f32 v41, v39, v41, v39
	v_fma_f32 v10, v6, v10, v6
	v_fma_f32 v8, v7, v8, v7
	v_add_f32_e32 v109, v109, v109
	v_mul_f32_e32 v40, 0x3f4c422a, v40
	v_mul_f32_e32 v41, 0x3f4c422a, v41
	v_mul_f32_e32 v10, 0x3f4c422a, v10
	v_mul_f32_e32 v8, 0x3f4c422a, v8
	v_mul_f32_e32 v109, 0xbfb8aa3b, v109
	v_add_f32_e32 v40, v40, v40
	v_add_f32_e32 v41, v41, v41
	v_add_f32_e32 v10, v10, v10
	v_add_f32_e32 v8, v8, v8
	v_exp_f32_e32 v109, v109
	v_mul_f32_e32 v40, 0xbfb8aa3b, v40
	v_mul_f32_e32 v41, 0xbfb8aa3b, v41
	v_mul_f32_e32 v10, 0xbfb8aa3b, v10
	v_mul_f32_e32 v8, 0xbfb8aa3b, v8
	v_exp_f32_e32 v40, v40
	v_exp_f32_e32 v41, v41
	v_exp_f32_e32 v10, v10
	v_exp_f32_e32 v8, v8
	v_add_f32_e32 v109, 1.0, v109
	v_rcp_f32_e32 v109, v109
	v_add_f32_e32 v40, 1.0, v40
	v_add_f32_e32 v41, 1.0, v41
	v_add_f32_e32 v10, 1.0, v10
	v_add_f32_e32 v8, 1.0, v8
	v_rcp_f32_e32 v40, v40
	v_rcp_f32_e32 v41, v41
	v_rcp_f32_e32 v10, v10
	v_rcp_f32_e32 v11, v8
	v_pk_mul_f32 v[42:43], v[44:45], v[66:67]
	v_pk_fma_f32 v[94:95], v[12:13], v[68:69], v[94:95]
	v_pk_fma_f32 v[36:37], v[36:37], v[84:85], v[42:43]
	v_lshlrev_b32_e32 v42, 16, v160
	v_and_b32_e32 v43, 0xffff0000, v160
	v_pk_add_f32 v[94:95], v[94:95], v[16:17]
	v_pk_mul_f32 v[72:73], v[72:73], v[108:109]
	v_pk_fma_f32 v[36:37], v[48:49], v[42:43], v[36:37]
	v_pk_mul_f32 v[72:73], v[94:95], v[72:73]
	v_pk_add_f32 v[36:37], v[36:37], v[56:57]
	v_pk_mul_f32 v[38:39], v[38:39], v[40:41]
	v_pk_add_f32 v[4:5], v[4:5], v[16:17]
	v_pk_mul_f32 v[6:7], v[6:7], v[10:11]
	v_cvt_pk_bf16_f32 v102, v102, v103
	v_cvt_pk_bf16_f32 v103, v104, v105
	v_cvt_pk_bf16_f32 v104, v106, v107
	v_cvt_pk_bf16_f32 v105, v72, v73
	v_mad_i64_i32 v[72:73], s[0:1], v163, s91, v[130:131]
	global_store_dwordx4 v[72:73], v[102:105], off sc1 nt
	s_nop 2
	v_pk_mul_f32 v[36:37], v[36:37], v[38:39]
	v_pk_mul_f32 v[8:9], v[4:5], v[6:7]
	v_cvt_pk_bf16_f32 v4, v34, v35
	v_cvt_pk_bf16_f32 v5, v36, v37
	v_cvt_pk_bf16_f32 v6, v2, v3
	v_cvt_pk_bf16_f32 v7, v8, v9
	v_mad_i64_i32 v[2:3], s[0:1], v155, s91, v[130:131]
	global_store_dwordx4 v[2:3], v[4:7], off sc1 nt
	s_nop 2
	s_andn2_b64 exec, exec, s[82:83]
	s_cbranch_execnz .LBB0_189
